# m28 + LayerNorm row-statistics: hipcc's SLP pattern (four v_mov to build operand pairs + v_pk_add_f32) replaced by the two scalar v_add_f32 it stands for (32 sites, 122 moves removed, same operand ord
# baseline (speedup 1.0000x reference)
.LBB0_536:
	s_lshl_b32 s0, s21, 5
	s_lshl_b32 s1, s62, 2
	s_add_u32 s8, s56, s1
	s_addc_u32 s9, s57, 0
	s_lshl_b32 s1, s60, 8
	s_or_b32 s0, s1, s0
	v_lshrrev_b32_e32 v130, 2, v166
	v_and_or_b32 v160, v130, 12, s0
	s_ashr_i32 s0, s19, 31
	s_lshr_b32 s0, s0, 28
	s_add_i32 s0, s19, s0
	s_ashr_i32 s0, s0, 4
	s_mul_hi_i32 s1, s0, 0x2400
	s_mulk_i32 s0, 0x2400
	s_lshl_b32 s24, s19, 8
	s_lshl_b64 s[62:63], s[0:1], 2
	s_add_u32 s0, s8, s62
	v_ashrrev_i32_e32 v161, 31, v160
	s_addc_u32 s1, s9, s63
	v_lshlrev_b64 v[142:143], 2, v[160:161]
	v_lshl_add_u64 v[130:131], s[0:1], 0, v[142:143]
	s_mov_b64 s[0:1], 0x100000
	v_lshl_add_u64 v[148:149], v[130:131], 0, s[0:1]
	s_mov_b32 s0, 0x100000
	v_add_co_u32_e32 v130, vcc, s0, v130
	s_barrier
	s_nop 0
	v_addc_co_u32_e32 v131, vcc, 0, v131, vcc
	global_load_dwordx4 v[132:135], v[130:131], off
	global_load_dwordx4 v[136:139], v[148:149], off offset:64
	global_load_dwordx4 v[210:213], v[148:149], off offset:512
	global_load_dwordx4 v[216:219], v[148:149], off offset:576
	s_add_i32 s0, s24, s35
	v_and_b32_e32 v168, 63, v166
	v_or_b32_e32 v144, s0, v167
	v_or_b32_e32 v146, 16, v144
	v_or_b32_e32 v148, 32, v144
	v_or_b32_e32 v150, 48, v144
	v_add_u32_e32 v152, 0x80, v144
	v_add_u32_e32 v154, 0x90, v144
	v_add_u32_e32 v156, 0xa0, v144
	v_add_u32_e32 v158, 0xb0, v144
	v_ashrrev_i32_e32 v145, 31, v144
	v_ashrrev_i32_e32 v147, 31, v146
	v_ashrrev_i32_e32 v149, 31, v148
	v_ashrrev_i32_e32 v151, 31, v150
	v_ashrrev_i32_e32 v153, 31, v152
	v_ashrrev_i32_e32 v155, 31, v154
	v_ashrrev_i32_e32 v157, 31, v156
	v_ashrrev_i32_e32 v159, 31, v158
	s_mov_b32 s0, 0x3f9837f0
	v_lshlrev_b64 v[248:249], 12, v[144:145]
	v_lshl_add_u64 v[248:249], s[64:65], 0, v[248:249]
	v_lshl_add_u64 v[248:249], v[248:249], 0, v[142:143]
	global_load_dwordx4 v[170:173], v[248:249], off
	global_load_dwordx4 v[174:177], v[248:249], off offset:64
	global_load_dwordx4 v[178:181], v[248:249], off offset:512
	global_load_dwordx4 v[182:185], v[248:249], off offset:576
	v_lshlrev_b64 v[248:249], 12, v[146:147]
	v_lshl_add_u64 v[248:249], s[64:65], 0, v[248:249]
	v_lshl_add_u64 v[248:249], v[248:249], 0, v[142:143]
	global_load_dwordx4 v[202:205], v[248:249], off
	global_load_dwordx4 v[206:209], v[248:249], off offset:64
	global_load_dwordx4 v[226:229], v[248:249], off offset:512
	global_load_dwordx4 v[230:233], v[248:249], off offset:576
	v_lshlrev_b64 v[248:249], 12, v[148:149]
	v_lshl_add_u64 v[248:249], s[64:65], 0, v[248:249]
	v_lshl_add_u64 v[248:249], v[248:249], 0, v[142:143]
	global_load_dwordx4 v[234:237], v[248:249], off
	global_load_dwordx4 v[238:241], v[248:249], off offset:64
	global_load_dwordx4 v[242:245], v[248:249], off offset:512
	s_waitcnt vmcnt(11)
	v_pk_mul_f32 v[130:131], v[134:135], 0.5 op_sel_hi:[1,0]
	v_pk_mul_f32 v[134:135], v[138:139], 0.5 op_sel_hi:[1,0]
	v_pk_mul_f32 v[138:139], v[212:213], 0.5 op_sel_hi:[1,0]
	v_pk_mul_f32 v[140:141], v[210:211], 0.5 op_sel_hi:[1,0]
	v_pk_mul_f32 v[132:133], v[132:133], 0.5 op_sel_hi:[1,0]
	v_pk_mul_f32 v[136:137], v[136:137], 0.5 op_sel_hi:[1,0]
	v_pk_mul_f32 v[164:165], v[216:217], 0.5 op_sel_hi:[1,0]
	v_pk_mul_f32 v[162:163], v[218:219], 0.5 op_sel_hi:[1,0]
	s_waitcnt vmcnt(10)
	v_pk_mul_f32 v[172:173], v[172:173], s[0:1] op_sel_hi:[1,0]
	v_pk_mul_f32 v[170:171], v[170:171], s[0:1] op_sel_hi:[1,0]
	v_pk_fma_f32 v[68:69], v[68:69], v[130:131], v[172:173]
	v_pk_fma_f32 v[66:67], v[66:67], v[132:133], v[170:171]
	global_load_dwordx4 v[170:173], v[248:249], off offset:576
	s_waitcnt vmcnt(10)
	v_pk_mul_f32 v[176:177], v[176:177], s[0:1] op_sel_hi:[1,0]
	v_pk_mul_f32 v[174:175], v[174:175], s[0:1] op_sel_hi:[1,0]
	v_pk_fma_f32 v[36:37], v[36:37], v[134:135], v[176:177]
	v_pk_fma_f32 v[34:35], v[34:35], v[136:137], v[174:175]
	v_lshlrev_b64 v[248:249], 12, v[150:151]
	v_lshl_add_u64 v[248:249], s[64:65], 0, v[248:249]
	v_lshl_add_u64 v[248:249], v[248:249], 0, v[142:143]
	global_load_dwordx4 v[174:177], v[248:249], off
	s_waitcnt vmcnt(10)
	v_pk_mul_f32 v[180:181], v[180:181], s[0:1] op_sel_hi:[1,0]
	v_pk_mul_f32 v[178:179], v[178:179], s[0:1] op_sel_hi:[1,0]
	v_pk_fma_f32 v[16:17], v[16:17], v[138:139], v[180:181]
	v_pk_fma_f32 v[14:15], v[14:15], v[140:141], v[178:179]
	global_load_dwordx4 v[178:181], v[248:249], off offset:64
	s_waitcnt vmcnt(10)
	v_pk_mul_f32 v[184:185], v[184:185], s[0:1] op_sel_hi:[1,0]
	v_pk_mul_f32 v[182:183], v[182:183], s[0:1] op_sel_hi:[1,0]
	v_pk_fma_f32 v[4:5], v[4:5], v[162:163], v[184:185]
	v_pk_fma_f32 v[2:3], v[2:3], v[164:165], v[182:183]
	global_load_dwordx4 v[182:185], v[248:249], off offset:512
	s_waitcnt vmcnt(10)
	v_pk_mul_f32 v[204:205], v[204:205], s[0:1] op_sel_hi:[1,0]
	v_pk_mul_f32 v[202:203], v[202:203], s[0:1] op_sel_hi:[1,0]
	v_pk_fma_f32 v[80:81], v[80:81], v[130:131], v[204:205]
	v_pk_fma_f32 v[78:79], v[78:79], v[132:133], v[202:203]
	global_load_dwordx4 v[202:205], v[248:249], off offset:576
	s_waitcnt vmcnt(10)
	v_pk_mul_f32 v[208:209], v[208:209], s[0:1] op_sel_hi:[1,0]
	v_pk_mul_f32 v[206:207], v[206:207], s[0:1] op_sel_hi:[1,0]
	v_pk_fma_f32 v[48:49], v[48:49], v[134:135], v[208:209]
	v_pk_fma_f32 v[46:47], v[46:47], v[136:137], v[206:207]
	v_lshlrev_b64 v[248:249], 12, v[152:153]
	v_lshl_add_u64 v[248:249], s[64:65], 0, v[248:249]
	v_lshl_add_u64 v[248:249], v[248:249], 0, v[142:143]
	global_load_dwordx4 v[206:209], v[248:249], off
	s_waitcnt vmcnt(10)
	v_pk_mul_f32 v[228:229], v[228:229], s[0:1] op_sel_hi:[1,0]
	v_pk_mul_f32 v[226:227], v[226:227], s[0:1] op_sel_hi:[1,0]
	v_pk_fma_f32 v[24:25], v[24:25], v[138:139], v[228:229]
	v_pk_fma_f32 v[22:23], v[22:23], v[140:141], v[226:227]
	global_load_dwordx4 v[226:229], v[248:249], off offset:64
	s_waitcnt vmcnt(10)
	v_pk_mul_f32 v[232:233], v[232:233], s[0:1] op_sel_hi:[1,0]
	v_pk_mul_f32 v[230:231], v[230:231], s[0:1] op_sel_hi:[1,0]
	v_pk_fma_f32 v[8:9], v[8:9], v[162:163], v[232:233]
	v_pk_fma_f32 v[6:7], v[6:7], v[164:165], v[230:231]
	global_load_dwordx4 v[230:233], v[248:249], off offset:512
	s_waitcnt vmcnt(10)
	v_pk_mul_f32 v[236:237], v[236:237], s[0:1] op_sel_hi:[1,0]
	v_pk_mul_f32 v[234:235], v[234:235], s[0:1] op_sel_hi:[1,0]
	v_pk_fma_f32 v[108:109], v[108:109], v[130:131], v[236:237]
	v_pk_fma_f32 v[106:107], v[106:107], v[132:133], v[234:235]
	global_load_dwordx4 v[234:237], v[248:249], off offset:576
	s_waitcnt vmcnt(10)
	v_pk_mul_f32 v[240:241], v[240:241], s[0:1] op_sel_hi:[1,0]
	v_pk_mul_f32 v[238:239], v[238:239], s[0:1] op_sel_hi:[1,0]
	v_pk_fma_f32 v[64:65], v[64:65], v[134:135], v[240:241]
	v_pk_fma_f32 v[62:63], v[62:63], v[136:137], v[238:239]
	v_lshlrev_b64 v[248:249], 12, v[154:155]
	v_lshl_add_u64 v[248:249], s[64:65], 0, v[248:249]
	v_lshl_add_u64 v[248:249], v[248:249], 0, v[142:143]
	global_load_dwordx4 v[238:241], v[248:249], off
	s_waitcnt vmcnt(10)
	v_pk_mul_f32 v[244:245], v[244:245], s[0:1] op_sel_hi:[1,0]
	v_pk_mul_f32 v[242:243], v[242:243], s[0:1] op_sel_hi:[1,0]
	v_pk_fma_f32 v[32:33], v[32:33], v[138:139], v[244:245]
	v_pk_fma_f32 v[30:31], v[30:31], v[140:141], v[242:243]
	global_load_dwordx4 v[242:245], v[248:249], off offset:64
	s_waitcnt vmcnt(10)
	v_pk_mul_f32 v[172:173], v[172:173], s[0:1] op_sel_hi:[1,0]
	v_pk_mul_f32 v[170:171], v[170:171], s[0:1] op_sel_hi:[1,0]
	v_pk_fma_f32 v[12:13], v[12:13], v[162:163], v[172:173]
	v_pk_fma_f32 v[10:11], v[10:11], v[164:165], v[170:171]
	global_load_dwordx4 v[170:173], v[248:249], off offset:512
	s_waitcnt vmcnt(10)
	v_pk_mul_f32 v[176:177], v[176:177], s[0:1] op_sel_hi:[1,0]
	v_pk_mul_f32 v[174:175], v[174:175], s[0:1] op_sel_hi:[1,0]
	v_pk_fma_f32 v[120:121], v[120:121], v[130:131], v[176:177]
	v_pk_fma_f32 v[118:119], v[118:119], v[132:133], v[174:175]
	global_load_dwordx4 v[174:177], v[248:249], off offset:576
	s_waitcnt vmcnt(10)
	v_pk_mul_f32 v[180:181], v[180:181], s[0:1] op_sel_hi:[1,0]
	v_pk_mul_f32 v[178:179], v[178:179], s[0:1] op_sel_hi:[1,0]
	v_pk_fma_f32 v[76:77], v[76:77], v[134:135], v[180:181]
	v_pk_fma_f32 v[74:75], v[74:75], v[136:137], v[178:179]
	v_lshlrev_b64 v[248:249], 12, v[156:157]
	v_lshl_add_u64 v[248:249], s[64:65], 0, v[248:249]
	v_lshl_add_u64 v[248:249], v[248:249], 0, v[142:143]
	global_load_dwordx4 v[178:181], v[248:249], off
	s_waitcnt vmcnt(10)
	v_pk_mul_f32 v[184:185], v[184:185], s[0:1] op_sel_hi:[1,0]
	v_pk_mul_f32 v[182:183], v[182:183], s[0:1] op_sel_hi:[1,0]
	v_pk_fma_f32 v[44:45], v[44:45], v[138:139], v[184:185]
	v_pk_fma_f32 v[42:43], v[42:43], v[140:141], v[182:183]
	global_load_dwordx4 v[182:185], v[248:249], off offset:64
	s_waitcnt vmcnt(10)
	v_pk_mul_f32 v[204:205], v[204:205], s[0:1] op_sel_hi:[1,0]
	v_pk_mul_f32 v[202:203], v[202:203], s[0:1] op_sel_hi:[1,0]
	v_pk_fma_f32 v[20:21], v[20:21], v[162:163], v[204:205]
	v_pk_fma_f32 v[18:19], v[18:19], v[164:165], v[202:203]
	global_load_dwordx4 v[202:205], v[248:249], off offset:512
	s_waitcnt vmcnt(10)
	v_pk_mul_f32 v[208:209], v[208:209], s[0:1] op_sel_hi:[1,0]
	v_pk_mul_f32 v[206:207], v[206:207], s[0:1] op_sel_hi:[1,0]
	v_pk_fma_f32 v[128:129], v[128:129], v[130:131], v[208:209]
	v_pk_fma_f32 v[126:127], v[126:127], v[132:133], v[206:207]
	global_load_dwordx4 v[206:209], v[248:249], off offset:576
	s_waitcnt vmcnt(10)
	v_pk_mul_f32 v[228:229], v[228:229], s[0:1] op_sel_hi:[1,0]
	v_pk_mul_f32 v[226:227], v[226:227], s[0:1] op_sel_hi:[1,0]
	v_pk_fma_f32 v[100:101], v[100:101], v[134:135], v[228:229]
	v_pk_fma_f32 v[98:99], v[98:99], v[136:137], v[226:227]
	v_lshlrev_b64 v[248:249], 12, v[158:159]
	v_lshl_add_u64 v[248:249], s[64:65], 0, v[248:249]
	v_lshl_add_u64 v[248:249], v[248:249], 0, v[142:143]
	global_load_dwordx4 v[226:229], v[248:249], off
	s_waitcnt vmcnt(10)
	v_pk_mul_f32 v[232:233], v[232:233], s[0:1] op_sel_hi:[1,0]
	v_pk_mul_f32 v[230:231], v[230:231], s[0:1] op_sel_hi:[1,0]
	v_pk_fma_f32 v[60:61], v[60:61], v[138:139], v[232:233]
	v_pk_fma_f32 v[58:59], v[58:59], v[140:141], v[230:231]
	global_load_dwordx4 v[230:233], v[248:249], off offset:64
	s_waitcnt vmcnt(10)
	v_pk_mul_f32 v[236:237], v[236:237], s[0:1] op_sel_hi:[1,0]
	v_pk_mul_f32 v[234:235], v[234:235], s[0:1] op_sel_hi:[1,0]
	v_pk_fma_f32 v[28:29], v[28:29], v[162:163], v[236:237]
	v_pk_fma_f32 v[26:27], v[26:27], v[164:165], v[234:235]
	global_load_dwordx4 v[234:237], v[248:249], off offset:512
	s_waitcnt vmcnt(10)
	v_pk_mul_f32 v[240:241], v[240:241], s[0:1] op_sel_hi:[1,0]
	v_pk_mul_f32 v[238:239], v[238:239], s[0:1] op_sel_hi:[1,0]
	v_pk_fma_f32 v[124:125], v[124:125], v[130:131], v[240:241]
	v_pk_fma_f32 v[122:123], v[122:123], v[132:133], v[238:239]
	global_load_dwordx4 v[238:241], v[248:249], off offset:576
	s_waitcnt vmcnt(10)
	v_pk_mul_f32 v[244:245], v[244:245], s[0:1] op_sel_hi:[1,0]
	v_pk_mul_f32 v[242:243], v[242:243], s[0:1] op_sel_hi:[1,0]
	v_pk_fma_f32 v[116:117], v[116:117], v[134:135], v[244:245]
	v_pk_fma_f32 v[114:115], v[114:115], v[136:137], v[242:243]
	s_waitcnt vmcnt(9)
	v_pk_mul_f32 v[172:173], v[172:173], s[0:1] op_sel_hi:[1,0]
	v_pk_mul_f32 v[170:171], v[170:171], s[0:1] op_sel_hi:[1,0]
	v_pk_fma_f32 v[72:73], v[72:73], v[138:139], v[172:173]
	v_pk_fma_f32 v[70:71], v[70:71], v[140:141], v[170:171]
	s_waitcnt vmcnt(8)
	v_pk_mul_f32 v[176:177], v[176:177], s[0:1] op_sel_hi:[1,0]
	v_pk_mul_f32 v[174:175], v[174:175], s[0:1] op_sel_hi:[1,0]
	v_pk_fma_f32 v[40:41], v[40:41], v[162:163], v[176:177]
	v_pk_fma_f32 v[38:39], v[38:39], v[164:165], v[174:175]
	s_waitcnt vmcnt(7)
	v_pk_mul_f32 v[180:181], v[180:181], s[0:1] op_sel_hi:[1,0]
	v_pk_mul_f32 v[178:179], v[178:179], s[0:1] op_sel_hi:[1,0]
	v_pk_fma_f32 v[112:113], v[112:113], v[130:131], v[180:181]
	v_pk_fma_f32 v[110:111], v[110:111], v[132:133], v[178:179]
	s_waitcnt vmcnt(6)
	v_pk_mul_f32 v[184:185], v[184:185], s[0:1] op_sel_hi:[1,0]
	v_pk_mul_f32 v[182:183], v[182:183], s[0:1] op_sel_hi:[1,0]
	v_pk_fma_f32 v[104:105], v[104:105], v[134:135], v[184:185]
	v_pk_fma_f32 v[102:103], v[102:103], v[136:137], v[182:183]
	s_waitcnt vmcnt(5)
	v_pk_mul_f32 v[204:205], v[204:205], s[0:1] op_sel_hi:[1,0]
	v_pk_mul_f32 v[202:203], v[202:203], s[0:1] op_sel_hi:[1,0]
	v_pk_fma_f32 v[88:89], v[88:89], v[138:139], v[204:205]
	v_pk_fma_f32 v[86:87], v[86:87], v[140:141], v[202:203]
	s_waitcnt vmcnt(4)
	v_pk_mul_f32 v[208:209], v[208:209], s[0:1] op_sel_hi:[1,0]
	v_pk_mul_f32 v[206:207], v[206:207], s[0:1] op_sel_hi:[1,0]
	v_pk_fma_f32 v[56:57], v[56:57], v[162:163], v[208:209]
	v_pk_fma_f32 v[54:55], v[54:55], v[164:165], v[206:207]
	s_waitcnt vmcnt(3)
	v_pk_mul_f32 v[228:229], v[228:229], s[0:1] op_sel_hi:[1,0]
	v_pk_mul_f32 v[226:227], v[226:227], s[0:1] op_sel_hi:[1,0]
	v_pk_fma_f32 v[96:97], v[96:97], v[130:131], v[228:229]
	v_pk_fma_f32 v[94:95], v[94:95], v[132:133], v[226:227]
	s_waitcnt vmcnt(2)
	v_pk_mul_f32 v[232:233], v[232:233], s[0:1] op_sel_hi:[1,0]
	v_pk_mul_f32 v[230:231], v[230:231], s[0:1] op_sel_hi:[1,0]
	v_pk_fma_f32 v[92:93], v[92:93], v[134:135], v[232:233]
	v_pk_fma_f32 v[90:91], v[90:91], v[136:137], v[230:231]
	s_waitcnt vmcnt(1)
	v_pk_mul_f32 v[236:237], v[236:237], s[0:1] op_sel_hi:[1,0]
	v_pk_mul_f32 v[234:235], v[234:235], s[0:1] op_sel_hi:[1,0]
	v_pk_fma_f32 v[84:85], v[84:85], v[138:139], v[236:237]
	v_pk_fma_f32 v[82:83], v[82:83], v[140:141], v[234:235]
	s_waitcnt vmcnt(0)
	v_pk_mul_f32 v[240:241], v[240:241], s[0:1] op_sel_hi:[1,0]
	v_pk_mul_f32 v[238:239], v[238:239], s[0:1] op_sel_hi:[1,0]
	v_pk_fma_f32 v[52:53], v[52:53], v[162:163], v[240:241]
	v_pk_fma_f32 v[50:51], v[50:51], v[164:165], v[238:239]
	v_mov_b32_e32 v134, v66
	v_mov_b32_e32 v135, v69
	v_mov_b32_e32 v136, v34
	v_mov_b32_e32 v137, v37
	v_add_f32_e32 v139, v16, v17
	v_mov_b32_e32 v138, v3
	v_and_b32_e32 v131, 64, v220
	v_xor_b32_e32 v130, 16, v220
	v_add_u32_e32 v131, 64, v131
	v_cmp_lt_i32_e32 vcc, v130, v131
	v_xor_b32_e32 v132, 32, v220
	v_cndmask_b32_e32 v130, v220, v130, vcc
	v_cmp_lt_i32_e32 vcc, v132, v131
	v_lshlrev_b32_e32 v130, 2, v130
	s_lshl_b32 s0, s21, 3
	v_cndmask_b32_e32 v131, v220, v132, vcc
	v_add_f32_e32 v132, v67, v134
	v_add_f32_e32 v133, v68, v135
	v_add_f32_e32 v134, v35, v136
	v_add_f32_e32 v135, v36, v137
	v_add_f32_e32 v132, v132, v133
	v_pk_add_f32 v[134:135], v[134:135], v[134:135] op_sel_hi:[0,1]
	v_add_f32_e32 v133, 0, v132
	v_add_f32_e32 v137, v14, v15
	v_mov_b32_e32 v136, v2
	v_mov_b32_e32 v134, v4
	v_mov_b32_e32 v132, v5
	v_pk_add_f32 v[136:137], v[136:137], v[138:139]
	v_pk_add_f32 v[132:133], v[134:135], v[132:133]
	v_lshlrev_b32_e32 v131, 2, v131
	v_pk_add_f32 v[132:133], v[136:137], v[132:133]
	v_cmp_gt_u32_e32 vcc, 16, v168
	v_add_f32_e32 v132, v132, v133
	ds_bpermute_b32 v133, v130, v132
	s_add_i32 s8, s0, 0
	s_waitcnt lgkmcnt(0)
	v_add_f32_e32 v132, v132, v133
	ds_bpermute_b32 v133, v131, v132
	s_waitcnt lgkmcnt(0)
	v_add_f32_e32 v132, v132, v133
	v_fmamk_f32 v134, v132, 0xbc800000, v69
	v_fmamk_f32 v136, v132, 0xbc800000, v67
	v_fmamk_f32 v133, v132, 0xbc800000, v68
	v_fmamk_f32 v135, v132, 0xbc800000, v66
	v_mul_f32_e32 v136, v136, v136
	v_mul_f32_e32 v134, v134, v134
	v_fmac_f32_e32 v136, v135, v135
	v_fmac_f32_e32 v134, v133, v133
	v_fmamk_f32 v135, v132, 0xbc800000, v37
	v_fmamk_f32 v137, v132, 0xbc800000, v35
	v_add_f32_e32 v133, v136, v134
	v_fmamk_f32 v134, v132, 0xbc800000, v36
	v_fmamk_f32 v136, v132, 0xbc800000, v34
	v_mul_f32_e32 v137, v137, v137
	v_mul_f32_e32 v135, v135, v135
	v_fmac_f32_e32 v137, v136, v136
	v_fmac_f32_e32 v135, v134, v134
	v_add_f32_e32 v134, v137, v135
	v_fmamk_f32 v135, v132, 0xbc800000, v17
	v_fmamk_f32 v137, v132, 0xbc800000, v15
	v_add_f32_e32 v133, v133, v134
	v_fmamk_f32 v134, v132, 0xbc800000, v16
	v_fmamk_f32 v136, v132, 0xbc800000, v14
	v_mul_f32_e32 v137, v137, v137
	v_mul_f32_e32 v135, v135, v135
	v_fmac_f32_e32 v137, v136, v136
	v_fmac_f32_e32 v135, v134, v134
	v_add_f32_e32 v134, v137, v135
	v_fmamk_f32 v135, v132, 0xbc800000, v5
	v_fmamk_f32 v137, v132, 0xbc800000, v3
	v_add_f32_e32 v133, v134, v133
	v_fmamk_f32 v134, v132, 0xbc800000, v4
	v_fmamk_f32 v136, v132, 0xbc800000, v2
	v_mul_f32_e32 v137, v137, v137
	v_mul_f32_e32 v135, v135, v135
	v_fmac_f32_e32 v137, v136, v136
	v_fmac_f32_e32 v135, v134, v134
	v_add_f32_e32 v134, v137, v135
	v_add_f32_e32 v133, v134, v133
	ds_bpermute_b32 v134, v130, v133
	s_waitcnt lgkmcnt(0)
	v_add_f32_e32 v133, v133, v134
	ds_bpermute_b32 v134, v131, v133
	s_and_saveexec_b64 s[0:1], vcc
	v_readlane_b32 s61, v251, 36
	s_mov_b64 s[70:71], 0x20000
	s_cbranch_execz .LBB0_538
	s_lshl_b32 s9, s20, 11
	s_add_i32 s9, s8, s9
	v_mul_f32_e32 v132, 0x3c800000, v132
	v_lshl_add_u32 v135, v167, 5, s9
	s_waitcnt lgkmcnt(0)
	v_add_f32_e32 v133, v133, v134
	ds_write_b64 v135, v[132:133]
.LBB0_538:
	s_or_b64 exec, exec, s[0:1]
	s_waitcnt lgkmcnt(0)
	v_add_f32_e32 v132, v79, v78
	v_add_f32_e32 v133, v80, v81
	v_add_f32_e32 v134, v47, v46
	v_add_f32_e32 v135, v48, v49
	v_add_f32_e32 v132, v132, v133
	v_pk_add_f32 v[134:135], v[134:135], v[134:135] op_sel_hi:[0,1]
	v_add_f32_e32 v133, 0, v132
	v_add_f32_e32 v137, v22, v23
	v_add_f32_e32 v139, v24, v25
	v_mov_b32_e32 v136, v6
	v_mov_b32_e32 v138, v7
	v_mov_b32_e32 v134, v8
	v_mov_b32_e32 v132, v9
	v_pk_add_f32 v[136:137], v[136:137], v[138:139]
	v_pk_add_f32 v[132:133], v[134:135], v[132:133]
	s_nop 0
	v_pk_add_f32 v[132:133], v[136:137], v[132:133]
	s_nop 0
	v_add_f32_e32 v132, v132, v133
	ds_bpermute_b32 v133, v130, v132
	s_waitcnt lgkmcnt(0)
	v_add_f32_e32 v132, v132, v133
	ds_bpermute_b32 v133, v131, v132
	s_waitcnt lgkmcnt(0)
	v_add_f32_e32 v132, v132, v133
	v_fmamk_f32 v134, v132, 0xbc800000, v81
	v_fmamk_f32 v136, v132, 0xbc800000, v79
	v_fmamk_f32 v133, v132, 0xbc800000, v80
	v_fmamk_f32 v135, v132, 0xbc800000, v78
	v_mul_f32_e32 v136, v136, v136
	v_mul_f32_e32 v134, v134, v134
	v_fmac_f32_e32 v136, v135, v135
	v_fmac_f32_e32 v134, v133, v133
	v_fmamk_f32 v135, v132, 0xbc800000, v49
	v_fmamk_f32 v137, v132, 0xbc800000, v47
	v_add_f32_e32 v133, v136, v134
	v_fmamk_f32 v134, v132, 0xbc800000, v48
	v_fmamk_f32 v136, v132, 0xbc800000, v46
	v_mul_f32_e32 v137, v137, v137
	v_mul_f32_e32 v135, v135, v135
	v_fmac_f32_e32 v137, v136, v136
	v_fmac_f32_e32 v135, v134, v134
	v_add_f32_e32 v134, v137, v135
	v_fmamk_f32 v135, v132, 0xbc800000, v25
	v_fmamk_f32 v137, v132, 0xbc800000, v23
	v_add_f32_e32 v133, v133, v134
	v_fmamk_f32 v134, v132, 0xbc800000, v24
	v_fmamk_f32 v136, v132, 0xbc800000, v22
	v_mul_f32_e32 v137, v137, v137
	v_mul_f32_e32 v135, v135, v135
	v_fmac_f32_e32 v137, v136, v136
	v_fmac_f32_e32 v135, v134, v134
	v_add_f32_e32 v134, v137, v135
	v_fmamk_f32 v135, v132, 0xbc800000, v9
	v_fmamk_f32 v137, v132, 0xbc800000, v7
	v_add_f32_e32 v133, v134, v133
	v_fmamk_f32 v134, v132, 0xbc800000, v8
	v_fmamk_f32 v136, v132, 0xbc800000, v6
	v_mul_f32_e32 v137, v137, v137
	v_mul_f32_e32 v135, v135, v135
	v_fmac_f32_e32 v137, v136, v136
	v_fmac_f32_e32 v135, v134, v134
	v_add_f32_e32 v134, v137, v135
	v_add_f32_e32 v133, v134, v133
	ds_bpermute_b32 v134, v130, v133
	s_waitcnt lgkmcnt(0)
	v_add_f32_e32 v133, v133, v134
	ds_bpermute_b32 v134, v131, v133
	s_and_saveexec_b64 s[0:1], vcc
	s_cbranch_execz .LBB0_540
	s_lshl_b32 s9, s20, 11
	s_add_i32 s9, s8, s9
	v_mul_f32_e32 v132, 0x3c800000, v132
	v_lshl_add_u32 v135, v167, 5, s9
	s_waitcnt lgkmcnt(0)
	v_add_f32_e32 v133, v133, v134
	ds_write_b64 v135, v[132:133] offset:512
.LBB0_540:
	s_or_b64 exec, exec, s[0:1]
	s_waitcnt lgkmcnt(0)
	v_add_f32_e32 v132, v107, v106
	v_add_f32_e32 v133, v108, v109
	v_add_f32_e32 v134, v63, v62
	v_add_f32_e32 v135, v64, v65
	v_add_f32_e32 v132, v132, v133
	v_pk_add_f32 v[134:135], v[134:135], v[134:135] op_sel_hi:[0,1]
	v_add_f32_e32 v133, 0, v132
	v_add_f32_e32 v137, v30, v31
	v_add_f32_e32 v139, v32, v33
	v_mov_b32_e32 v136, v10
	v_mov_b32_e32 v138, v11
	v_mov_b32_e32 v134, v12
	v_mov_b32_e32 v132, v13
	v_pk_add_f32 v[136:137], v[136:137], v[138:139]
	v_pk_add_f32 v[132:133], v[134:135], v[132:133]
	s_nop 0
	v_pk_add_f32 v[132:133], v[136:137], v[132:133]
	s_nop 0
	v_add_f32_e32 v132, v132, v133
	ds_bpermute_b32 v133, v130, v132
	s_waitcnt lgkmcnt(0)
	v_add_f32_e32 v132, v132, v133
	ds_bpermute_b32 v133, v131, v132
	s_waitcnt lgkmcnt(0)
	v_add_f32_e32 v132, v132, v133
	v_fmamk_f32 v134, v132, 0xbc800000, v109
	v_fmamk_f32 v136, v132, 0xbc800000, v107
	v_fmamk_f32 v133, v132, 0xbc800000, v108
	v_fmamk_f32 v135, v132, 0xbc800000, v106
	v_mul_f32_e32 v136, v136, v136
	v_mul_f32_e32 v134, v134, v134
	v_fmac_f32_e32 v136, v135, v135
	v_fmac_f32_e32 v134, v133, v133
	v_fmamk_f32 v135, v132, 0xbc800000, v65
	v_fmamk_f32 v137, v132, 0xbc800000, v63
	v_add_f32_e32 v133, v136, v134
	v_fmamk_f32 v134, v132, 0xbc800000, v64
	v_fmamk_f32 v136, v132, 0xbc800000, v62
	v_mul_f32_e32 v137, v137, v137
	v_mul_f32_e32 v135, v135, v135
	v_fmac_f32_e32 v137, v136, v136
	v_fmac_f32_e32 v135, v134, v134
	v_add_f32_e32 v134, v137, v135
	v_fmamk_f32 v135, v132, 0xbc800000, v33
	v_fmamk_f32 v137, v132, 0xbc800000, v31
	v_add_f32_e32 v133, v133, v134
	v_fmamk_f32 v134, v132, 0xbc800000, v32
	v_fmamk_f32 v136, v132, 0xbc800000, v30
	v_mul_f32_e32 v137, v137, v137
	v_mul_f32_e32 v135, v135, v135
	v_fmac_f32_e32 v137, v136, v136
	v_fmac_f32_e32 v135, v134, v134
	v_add_f32_e32 v134, v137, v135
	v_fmamk_f32 v135, v132, 0xbc800000, v13
	v_fmamk_f32 v137, v132, 0xbc800000, v11
	v_add_f32_e32 v133, v134, v133
	v_fmamk_f32 v134, v132, 0xbc800000, v12
	v_fmamk_f32 v136, v132, 0xbc800000, v10
	v_mul_f32_e32 v137, v137, v137
	v_mul_f32_e32 v135, v135, v135
	v_fmac_f32_e32 v137, v136, v136
	v_fmac_f32_e32 v135, v134, v134
	v_add_f32_e32 v134, v137, v135
	v_add_f32_e32 v133, v134, v133
	ds_bpermute_b32 v134, v130, v133
	s_waitcnt lgkmcnt(0)
	v_add_f32_e32 v133, v133, v134
	ds_bpermute_b32 v134, v131, v133
	s_and_saveexec_b64 s[0:1], vcc
	s_cbranch_execz .LBB0_542
	s_lshl_b32 s9, s20, 11
	s_add_i32 s9, s8, s9
	v_mul_f32_e32 v132, 0x3c800000, v132
	v_lshl_add_u32 v135, v167, 5, s9
	s_waitcnt lgkmcnt(0)
	v_add_f32_e32 v133, v133, v134
	ds_write_b64 v135, v[132:133] offset:1024
.LBB0_542:
	s_or_b64 exec, exec, s[0:1]
	s_waitcnt lgkmcnt(0)
	v_add_f32_e32 v132, v119, v118
	v_add_f32_e32 v133, v120, v121
	v_add_f32_e32 v134, v75, v74
	v_add_f32_e32 v135, v76, v77
	v_add_f32_e32 v132, v132, v133
	v_pk_add_f32 v[134:135], v[134:135], v[134:135] op_sel_hi:[0,1]
	v_add_f32_e32 v133, 0, v132
	v_add_f32_e32 v137, v42, v43
	v_add_f32_e32 v139, v44, v45
	v_mov_b32_e32 v136, v18
	v_mov_b32_e32 v138, v19
	v_mov_b32_e32 v134, v20
	v_mov_b32_e32 v132, v21
	v_pk_add_f32 v[136:137], v[136:137], v[138:139]
	v_pk_add_f32 v[132:133], v[134:135], v[132:133]
	s_nop 0
	v_pk_add_f32 v[132:133], v[136:137], v[132:133]
	s_nop 0
	v_add_f32_e32 v132, v132, v133
	ds_bpermute_b32 v133, v130, v132
	s_waitcnt lgkmcnt(0)
	v_add_f32_e32 v132, v132, v133
	ds_bpermute_b32 v133, v131, v132
	s_waitcnt lgkmcnt(0)
	v_add_f32_e32 v132, v132, v133
	v_fmamk_f32 v134, v132, 0xbc800000, v121
	v_fmamk_f32 v136, v132, 0xbc800000, v119
	v_fmamk_f32 v133, v132, 0xbc800000, v120
	v_fmamk_f32 v135, v132, 0xbc800000, v118
	v_mul_f32_e32 v136, v136, v136
	v_mul_f32_e32 v134, v134, v134
	v_fmac_f32_e32 v136, v135, v135
	v_fmac_f32_e32 v134, v133, v133
	v_fmamk_f32 v135, v132, 0xbc800000, v77
	v_fmamk_f32 v137, v132, 0xbc800000, v75
	v_add_f32_e32 v133, v136, v134
	v_fmamk_f32 v134, v132, 0xbc800000, v76
	v_fmamk_f32 v136, v132, 0xbc800000, v74
	v_mul_f32_e32 v137, v137, v137
	v_mul_f32_e32 v135, v135, v135
	v_fmac_f32_e32 v137, v136, v136
	v_fmac_f32_e32 v135, v134, v134
	v_add_f32_e32 v134, v137, v135
	v_fmamk_f32 v135, v132, 0xbc800000, v45
	v_fmamk_f32 v137, v132, 0xbc800000, v43
	v_add_f32_e32 v133, v133, v134
	v_fmamk_f32 v134, v132, 0xbc800000, v44
	v_fmamk_f32 v136, v132, 0xbc800000, v42
	v_mul_f32_e32 v137, v137, v137
	v_mul_f32_e32 v135, v135, v135
	v_fmac_f32_e32 v137, v136, v136
	v_fmac_f32_e32 v135, v134, v134
	v_add_f32_e32 v134, v137, v135
	v_fmamk_f32 v135, v132, 0xbc800000, v21
	v_fmamk_f32 v137, v132, 0xbc800000, v19
	v_add_f32_e32 v133, v134, v133
	v_fmamk_f32 v134, v132, 0xbc800000, v20
	v_fmamk_f32 v136, v132, 0xbc800000, v18
	v_mul_f32_e32 v137, v137, v137
	v_mul_f32_e32 v135, v135, v135
	v_fmac_f32_e32 v137, v136, v136
	v_fmac_f32_e32 v135, v134, v134
	v_add_f32_e32 v134, v137, v135
	v_add_f32_e32 v133, v134, v133
	ds_bpermute_b32 v134, v130, v133
	s_waitcnt lgkmcnt(0)
	v_add_f32_e32 v133, v133, v134
	ds_bpermute_b32 v134, v131, v133
	s_and_saveexec_b64 s[0:1], vcc
	s_cbranch_execz .LBB0_544
	s_lshl_b32 s9, s20, 11
	s_add_i32 s9, s8, s9
	v_mul_f32_e32 v132, 0x3c800000, v132
	v_lshl_add_u32 v135, v167, 5, s9
	s_waitcnt lgkmcnt(0)
	v_add_f32_e32 v133, v133, v134
	ds_write_b64 v135, v[132:133] offset:1536
.LBB0_544:
	s_or_b64 exec, exec, s[0:1]
	s_waitcnt lgkmcnt(0)
	v_add_f32_e32 v132, v127, v126
	v_add_f32_e32 v133, v128, v129
	v_add_f32_e32 v134, v99, v98
	v_add_f32_e32 v135, v100, v101
	v_add_f32_e32 v132, v132, v133
	v_pk_add_f32 v[134:135], v[134:135], v[134:135] op_sel_hi:[0,1]
	v_add_f32_e32 v133, 0, v132
	v_add_f32_e32 v137, v58, v59
	v_add_f32_e32 v139, v60, v61
	v_mov_b32_e32 v136, v26
	v_mov_b32_e32 v138, v27
	v_mov_b32_e32 v134, v28
	v_mov_b32_e32 v132, v29
	v_pk_add_f32 v[136:137], v[136:137], v[138:139]
	v_pk_add_f32 v[132:133], v[134:135], v[132:133]
	s_nop 0
	v_pk_add_f32 v[132:133], v[136:137], v[132:133]
	s_nop 0
	v_add_f32_e32 v132, v132, v133
	ds_bpermute_b32 v133, v130, v132
	s_waitcnt lgkmcnt(0)
	v_add_f32_e32 v132, v132, v133
	ds_bpermute_b32 v133, v131, v132
	s_waitcnt lgkmcnt(0)
	v_add_f32_e32 v132, v132, v133
	v_fmamk_f32 v134, v132, 0xbc800000, v129
	v_fmamk_f32 v136, v132, 0xbc800000, v127
	v_fmamk_f32 v133, v132, 0xbc800000, v128
	v_fmamk_f32 v135, v132, 0xbc800000, v126
	v_mul_f32_e32 v136, v136, v136
	v_mul_f32_e32 v134, v134, v134
	v_fmac_f32_e32 v136, v135, v135
	v_fmac_f32_e32 v134, v133, v133
	v_fmamk_f32 v135, v132, 0xbc800000, v101
	v_fmamk_f32 v137, v132, 0xbc800000, v99
	v_add_f32_e32 v133, v136, v134
	v_fmamk_f32 v134, v132, 0xbc800000, v100
	v_fmamk_f32 v136, v132, 0xbc800000, v98
	v_mul_f32_e32 v137, v137, v137
	v_mul_f32_e32 v135, v135, v135
	v_fmac_f32_e32 v137, v136, v136
	v_fmac_f32_e32 v135, v134, v134
	v_add_f32_e32 v134, v137, v135
	v_fmamk_f32 v135, v132, 0xbc800000, v61
	v_fmamk_f32 v137, v132, 0xbc800000, v59
	v_add_f32_e32 v133, v133, v134
	v_fmamk_f32 v134, v132, 0xbc800000, v60
	v_fmamk_f32 v136, v132, 0xbc800000, v58
	v_mul_f32_e32 v137, v137, v137
	v_mul_f32_e32 v135, v135, v135
	v_fmac_f32_e32 v137, v136, v136
	v_fmac_f32_e32 v135, v134, v134
	v_add_f32_e32 v134, v137, v135
	v_fmamk_f32 v135, v132, 0xbc800000, v29
	v_fmamk_f32 v137, v132, 0xbc800000, v27
	v_add_f32_e32 v133, v134, v133
	v_fmamk_f32 v134, v132, 0xbc800000, v28
	v_fmamk_f32 v136, v132, 0xbc800000, v26
	v_mul_f32_e32 v137, v137, v137
	v_mul_f32_e32 v135, v135, v135
	v_fmac_f32_e32 v137, v136, v136
	v_fmac_f32_e32 v135, v134, v134
	v_add_f32_e32 v134, v137, v135
	v_add_f32_e32 v133, v134, v133
	ds_bpermute_b32 v134, v130, v133
	s_waitcnt lgkmcnt(0)
	v_add_f32_e32 v133, v133, v134
	ds_bpermute_b32 v134, v131, v133
	s_and_saveexec_b64 s[0:1], vcc
	s_cbranch_execz .LBB0_546
	s_lshl_b32 s9, s20, 11
	s_add_i32 s9, s8, s9
	v_mul_f32_e32 v132, 0x3c800000, v132
	v_lshl_add_u32 v135, v167, 5, s9
	s_waitcnt lgkmcnt(0)
	v_add_f32_e32 v133, v133, v134
	ds_write_b64 v135, v[132:133] offset:4096
.LBB0_546:
	s_or_b64 exec, exec, s[0:1]
	s_waitcnt lgkmcnt(0)
	v_add_f32_e32 v132, v123, v122
	v_add_f32_e32 v133, v124, v125
	v_add_f32_e32 v134, v115, v114
	v_add_f32_e32 v135, v116, v117
	v_add_f32_e32 v132, v132, v133
	v_pk_add_f32 v[134:135], v[134:135], v[134:135] op_sel_hi:[0,1]
	v_add_f32_e32 v133, 0, v132
	v_add_f32_e32 v137, v70, v71
	v_add_f32_e32 v139, v72, v73
	v_mov_b32_e32 v136, v38
	v_mov_b32_e32 v138, v39
	v_mov_b32_e32 v134, v40
	v_mov_b32_e32 v132, v41
	v_pk_add_f32 v[136:137], v[136:137], v[138:139]
	v_pk_add_f32 v[132:133], v[134:135], v[132:133]
	s_nop 0
	v_pk_add_f32 v[132:133], v[136:137], v[132:133]
	s_nop 0
	v_add_f32_e32 v132, v132, v133
	ds_bpermute_b32 v133, v130, v132
	s_waitcnt lgkmcnt(0)
	v_add_f32_e32 v132, v132, v133
	ds_bpermute_b32 v133, v131, v132
	s_waitcnt lgkmcnt(0)
	v_add_f32_e32 v132, v132, v133
	v_fmamk_f32 v134, v132, 0xbc800000, v125
	v_fmamk_f32 v136, v132, 0xbc800000, v123
	v_fmamk_f32 v133, v132, 0xbc800000, v124
	v_fmamk_f32 v135, v132, 0xbc800000, v122
	v_mul_f32_e32 v136, v136, v136
	v_mul_f32_e32 v134, v134, v134
	v_fmac_f32_e32 v136, v135, v135
	v_fmac_f32_e32 v134, v133, v133
	v_fmamk_f32 v135, v132, 0xbc800000, v117
	v_fmamk_f32 v137, v132, 0xbc800000, v115
	v_add_f32_e32 v133, v136, v134
	v_fmamk_f32 v134, v132, 0xbc800000, v116
	v_fmamk_f32 v136, v132, 0xbc800000, v114
	v_mul_f32_e32 v137, v137, v137
	v_mul_f32_e32 v135, v135, v135
	v_fmac_f32_e32 v137, v136, v136
	v_fmac_f32_e32 v135, v134, v134
	v_add_f32_e32 v134, v137, v135
	v_fmamk_f32 v135, v132, 0xbc800000, v73
	v_fmamk_f32 v137, v132, 0xbc800000, v71
	v_add_f32_e32 v133, v133, v134
	v_fmamk_f32 v134, v132, 0xbc800000, v72
	v_fmamk_f32 v136, v132, 0xbc800000, v70
	v_mul_f32_e32 v137, v137, v137
	v_mul_f32_e32 v135, v135, v135
	v_fmac_f32_e32 v137, v136, v136
	v_fmac_f32_e32 v135, v134, v134
	v_add_f32_e32 v134, v137, v135
	v_fmamk_f32 v135, v132, 0xbc800000, v41
	v_fmamk_f32 v137, v132, 0xbc800000, v39
	v_add_f32_e32 v133, v134, v133
	v_fmamk_f32 v134, v132, 0xbc800000, v40
	v_fmamk_f32 v136, v132, 0xbc800000, v38
	v_mul_f32_e32 v137, v137, v137
	v_mul_f32_e32 v135, v135, v135
	v_fmac_f32_e32 v137, v136, v136
	v_fmac_f32_e32 v135, v134, v134
	v_add_f32_e32 v134, v137, v135
	v_add_f32_e32 v133, v134, v133
	ds_bpermute_b32 v134, v130, v133
	s_waitcnt lgkmcnt(0)
	v_add_f32_e32 v133, v133, v134
	ds_bpermute_b32 v134, v131, v133
	s_and_saveexec_b64 s[0:1], vcc
	s_cbranch_execz .LBB0_548
	s_lshl_b32 s9, s20, 11
	s_add_i32 s9, s8, s9
	v_mul_f32_e32 v132, 0x3c800000, v132
	v_lshl_add_u32 v135, v167, 5, s9
	s_waitcnt lgkmcnt(0)
	v_add_f32_e32 v133, v133, v134
	ds_write_b64 v135, v[132:133] offset:4608
.LBB0_548:
	s_or_b64 exec, exec, s[0:1]
	s_waitcnt lgkmcnt(0)
	v_add_f32_e32 v132, v111, v110
	v_add_f32_e32 v133, v112, v113
	v_add_f32_e32 v134, v103, v102
	v_add_f32_e32 v135, v104, v105
	v_add_f32_e32 v132, v132, v133
	v_pk_add_f32 v[134:135], v[134:135], v[134:135] op_sel_hi:[0,1]
	v_add_f32_e32 v133, 0, v132
	v_add_f32_e32 v137, v86, v87
	v_add_f32_e32 v139, v88, v89
	v_mov_b32_e32 v136, v54
	v_mov_b32_e32 v138, v55
	v_mov_b32_e32 v134, v56
	v_mov_b32_e32 v132, v57
	v_pk_add_f32 v[136:137], v[136:137], v[138:139]
	v_pk_add_f32 v[132:133], v[134:135], v[132:133]
	s_nop 0
	v_pk_add_f32 v[132:133], v[136:137], v[132:133]
	s_nop 0
	v_add_f32_e32 v132, v132, v133
	ds_bpermute_b32 v133, v130, v132
	s_waitcnt lgkmcnt(0)
	v_add_f32_e32 v132, v132, v133
	ds_bpermute_b32 v133, v131, v132
	s_waitcnt lgkmcnt(0)
	v_add_f32_e32 v132, v132, v133
	v_fmamk_f32 v134, v132, 0xbc800000, v113
	v_fmamk_f32 v136, v132, 0xbc800000, v111
	v_fmamk_f32 v133, v132, 0xbc800000, v112
	v_fmamk_f32 v135, v132, 0xbc800000, v110
	v_mul_f32_e32 v136, v136, v136
	v_mul_f32_e32 v134, v134, v134
	v_fmac_f32_e32 v136, v135, v135
	v_fmac_f32_e32 v134, v133, v133
	v_fmamk_f32 v135, v132, 0xbc800000, v105
	v_fmamk_f32 v137, v132, 0xbc800000, v103
	v_add_f32_e32 v133, v136, v134
	v_fmamk_f32 v134, v132, 0xbc800000, v104
	v_fmamk_f32 v136, v132, 0xbc800000, v102
	v_mul_f32_e32 v137, v137, v137
	v_mul_f32_e32 v135, v135, v135
	v_fmac_f32_e32 v137, v136, v136
	v_fmac_f32_e32 v135, v134, v134
	v_add_f32_e32 v134, v137, v135
	v_fmamk_f32 v135, v132, 0xbc800000, v89
	v_fmamk_f32 v137, v132, 0xbc800000, v87
	v_add_f32_e32 v133, v133, v134
	v_fmamk_f32 v134, v132, 0xbc800000, v88
	v_fmamk_f32 v136, v132, 0xbc800000, v86
	v_mul_f32_e32 v137, v137, v137
	v_mul_f32_e32 v135, v135, v135
	v_fmac_f32_e32 v137, v136, v136
	v_fmac_f32_e32 v135, v134, v134
	v_add_f32_e32 v134, v137, v135
	v_fmamk_f32 v135, v132, 0xbc800000, v57
	v_fmamk_f32 v137, v132, 0xbc800000, v55
	v_add_f32_e32 v133, v134, v133
	v_fmamk_f32 v134, v132, 0xbc800000, v56
	v_fmamk_f32 v136, v132, 0xbc800000, v54
	v_mul_f32_e32 v137, v137, v137
	v_mul_f32_e32 v135, v135, v135
	v_fmac_f32_e32 v137, v136, v136
	v_fmac_f32_e32 v135, v134, v134
	v_add_f32_e32 v134, v137, v135
	v_add_f32_e32 v133, v134, v133
	ds_bpermute_b32 v134, v130, v133
	s_waitcnt lgkmcnt(0)
	v_add_f32_e32 v133, v133, v134
	ds_bpermute_b32 v134, v131, v133
	s_and_saveexec_b64 s[0:1], vcc
	s_cbranch_execz .LBB0_550
	s_lshl_b32 s9, s20, 11
	s_add_i32 s9, s8, s9
	v_mul_f32_e32 v132, 0x3c800000, v132
	v_lshl_add_u32 v135, v167, 5, s9
	s_waitcnt lgkmcnt(0)
	v_add_f32_e32 v133, v133, v134
	ds_write_b64 v135, v[132:133] offset:5120
.LBB0_550:
	s_or_b64 exec, exec, s[0:1]
	s_waitcnt lgkmcnt(0)
	v_add_f32_e32 v132, v95, v94
	v_add_f32_e32 v133, v96, v97
	v_add_f32_e32 v134, v91, v90
	v_add_f32_e32 v135, v92, v93
	v_add_f32_e32 v132, v132, v133
	v_pk_add_f32 v[134:135], v[134:135], v[134:135] op_sel_hi:[0,1]
	v_add_f32_e32 v133, 0, v132
	v_add_f32_e32 v137, v82, v83
	v_add_f32_e32 v139, v84, v85
	v_mov_b32_e32 v136, v50
	v_mov_b32_e32 v138, v51
	v_mov_b32_e32 v134, v52
	v_mov_b32_e32 v132, v53
	v_pk_add_f32 v[136:137], v[136:137], v[138:139]
	v_pk_add_f32 v[132:133], v[134:135], v[132:133]
	s_nop 0
	v_pk_add_f32 v[132:133], v[136:137], v[132:133]
	s_nop 0
	v_add_f32_e32 v132, v132, v133
	ds_bpermute_b32 v133, v130, v132
	s_waitcnt lgkmcnt(0)
	v_add_f32_e32 v132, v132, v133
	ds_bpermute_b32 v133, v131, v132
	s_waitcnt lgkmcnt(0)
	v_add_f32_e32 v132, v132, v133
	v_fmamk_f32 v134, v132, 0xbc800000, v97
	v_fmamk_f32 v136, v132, 0xbc800000, v95
	v_fmamk_f32 v133, v132, 0xbc800000, v96
	v_fmamk_f32 v135, v132, 0xbc800000, v94
	v_mul_f32_e32 v136, v136, v136
	v_mul_f32_e32 v134, v134, v134
	v_fmac_f32_e32 v136, v135, v135
	v_fmac_f32_e32 v134, v133, v133
	v_fmamk_f32 v135, v132, 0xbc800000, v93
	v_fmamk_f32 v137, v132, 0xbc800000, v91
	v_add_f32_e32 v133, v136, v134
	v_fmamk_f32 v134, v132, 0xbc800000, v92
	v_fmamk_f32 v136, v132, 0xbc800000, v90
	v_mul_f32_e32 v137, v137, v137
	v_mul_f32_e32 v135, v135, v135
	v_fmac_f32_e32 v137, v136, v136
	v_fmac_f32_e32 v135, v134, v134
	v_add_f32_e32 v134, v137, v135
	v_fmamk_f32 v135, v132, 0xbc800000, v85
	v_fmamk_f32 v137, v132, 0xbc800000, v83
	v_add_f32_e32 v133, v133, v134
	v_fmamk_f32 v134, v132, 0xbc800000, v84
	v_fmamk_f32 v136, v132, 0xbc800000, v82
	v_mul_f32_e32 v137, v137, v137
	v_mul_f32_e32 v135, v135, v135
	v_fmac_f32_e32 v137, v136, v136
	v_fmac_f32_e32 v135, v134, v134
	v_add_f32_e32 v134, v137, v135
	v_fmamk_f32 v135, v132, 0xbc800000, v53
	v_fmamk_f32 v137, v132, 0xbc800000, v51
	v_add_f32_e32 v133, v134, v133
	v_fmamk_f32 v134, v132, 0xbc800000, v52
	v_fmamk_f32 v136, v132, 0xbc800000, v50
	v_mul_f32_e32 v137, v137, v137
	v_mul_f32_e32 v135, v135, v135
	v_fmac_f32_e32 v137, v136, v136
	v_fmac_f32_e32 v135, v134, v134
	v_add_f32_e32 v134, v137, v135
	v_add_f32_e32 v133, v134, v133
	ds_bpermute_b32 v130, v130, v133
	s_waitcnt lgkmcnt(0)
	v_add_f32_e32 v130, v133, v130
	ds_bpermute_b32 v131, v131, v130
	s_and_saveexec_b64 s[0:1], vcc
	s_cbranch_execz .LBB0_552
	s_lshl_b32 s9, s20, 11
	s_add_i32 s8, s8, s9
	v_mul_f32_e32 v132, 0x3c800000, v132
	v_lshl_add_u32 v134, v167, 5, s8
	s_waitcnt lgkmcnt(0)
	v_add_f32_e32 v133, v130, v131
	ds_write_b64 v134, v[132:133] offset:5632

.LBB0_3244:
	s_lshl_b32 s0, s18, 5
	s_lshl_b32 s1, s42, 8
	s_or_b32 s0, s1, s0
	v_lshrrev_b32_e32 v130, 2, v167
	v_and_or_b32 v162, v130, 12, s0
	s_ashr_i32 s0, s16, 31
	s_lshr_b32 s0, s0, 28
	s_add_i32 s0, s16, s0
	s_ashr_i32 s0, s0, 4
	s_mul_hi_i32 s1, s0, 0x2400
	s_mulk_i32 s0, 0x2400
	s_lshl_b32 s19, s16, 8
	s_lshl_b64 s[52:53], s[0:1], 2
	s_add_u32 s0, s6, s52
	v_ashrrev_i32_e32 v163, 31, v162
	s_addc_u32 s1, s7, s53
	v_lshlrev_b64 v[164:165], 2, v[162:163]
	v_lshl_add_u64 v[130:131], s[0:1], 0, v[164:165]
	s_add_i32 s0, s19, s20
	v_or_b32_e32 v160, s0, v168
	v_ashrrev_i32_e32 v161, 31, v160
	v_lshlrev_b64 v[132:133], 12, v[160:161]
	v_lshl_add_u64 v[132:133], s[44:45], 0, v[132:133]
	s_mov_b32 s0, 0x105000
	v_lshl_add_u64 v[146:147], v[132:133], 0, v[164:165]
	v_add_co_u32_e32 v132, vcc, s0, v130
	s_mov_b64 s[0:1], 0x105000
	s_nop 0
	v_addc_co_u32_e32 v133, vcc, 0, v131, vcc
	v_lshl_add_u64 v[130:131], v[130:131], 0, s[0:1]
	global_load_dwordx4 v[134:137], v[132:133], off
	global_load_dwordx4 v[142:145], v[130:131], off offset:64
	global_load_dwordx4 v[138:141], v[130:131], off offset:512
	s_nop 0
	global_load_dwordx4 v[130:133], v[130:131], off offset:576
	s_mov_b32 s0, 0x3f9837f0
	v_and_b32_e32 v169, 64, v220
	v_xor_b32_e32 v161, 16, v220
	v_add_u32_e32 v188, 64, v169
	v_cmp_lt_i32_e32 vcc, v161, v188
	global_load_dwordx4 v[170:173], v[146:147], off
	global_load_dwordx4 v[174:177], v[146:147], off offset:64
	global_load_dwordx4 v[178:181], v[146:147], off offset:512
	global_load_dwordx4 v[182:185], v[146:147], off offset:576
	v_or_b32_e32 v148, 16, v160
	v_ashrrev_i32_e32 v149, 31, v148
	v_lshlrev_b64 v[148:149], 12, v[148:149]
	v_lshl_add_u64 v[148:149], s[44:45], 0, v[148:149]
	v_lshl_add_u64 v[148:149], v[148:149], 0, v[164:165]
	global_load_dwordx4 v[226:229], v[148:149], off
	global_load_dwordx4 v[230:233], v[148:149], off offset:64
	global_load_dwordx4 v[234:237], v[148:149], off offset:512
	global_load_dwordx4 v[238:241], v[148:149], off offset:576
	v_or_b32_e32 v150, 32, v160
	v_ashrrev_i32_e32 v151, 31, v150
	v_lshlrev_b64 v[150:151], 12, v[150:151]
	v_lshl_add_u64 v[150:151], s[44:45], 0, v[150:151]
	v_lshl_add_u64 v[150:151], v[150:151], 0, v[164:165]
	global_load_dwordx4 v[242:245], v[150:151], off
	global_load_dwordx4 v[200:203], v[150:151], off offset:64
	global_load_dwordx4 v[204:207], v[150:151], off offset:512
	s_waitcnt vmcnt(10)
	v_pk_mul_f32 v[172:173], v[172:173], s[0:1] op_sel_hi:[1,0]
	v_pk_mul_f32 v[170:171], v[170:171], s[0:1] op_sel_hi:[1,0]
	v_pk_fma_f32 v[128:129], v[128:129], v[136:137], v[172:173]
	v_pk_fma_f32 v[126:127], v[126:127], v[134:135], v[170:171]
	global_load_dwordx4 v[170:173], v[150:151], off offset:576
	s_waitcnt vmcnt(10)
	v_pk_mul_f32 v[176:177], v[176:177], s[0:1] op_sel_hi:[1,0]
	v_pk_mul_f32 v[174:175], v[174:175], s[0:1] op_sel_hi:[1,0]
	v_pk_fma_f32 v[68:69], v[68:69], v[144:145], v[176:177]
	v_pk_fma_f32 v[66:67], v[66:67], v[142:143], v[174:175]
	v_or_b32_e32 v152, 48, v160
	v_ashrrev_i32_e32 v153, 31, v152
	v_lshlrev_b64 v[152:153], 12, v[152:153]
	v_lshl_add_u64 v[152:153], s[44:45], 0, v[152:153]
	v_lshl_add_u64 v[152:153], v[152:153], 0, v[164:165]
	global_load_dwordx4 v[174:177], v[152:153], off
	s_waitcnt vmcnt(10)
	v_pk_mul_f32 v[180:181], v[180:181], s[0:1] op_sel_hi:[1,0]
	v_pk_mul_f32 v[178:179], v[178:179], s[0:1] op_sel_hi:[1,0]
	v_pk_fma_f32 v[36:37], v[36:37], v[140:141], v[180:181]
	v_pk_fma_f32 v[34:35], v[34:35], v[138:139], v[178:179]
	global_load_dwordx4 v[178:181], v[152:153], off offset:64
	s_waitcnt vmcnt(10)
	v_pk_mul_f32 v[184:185], v[184:185], s[0:1] op_sel_hi:[1,0]
	v_pk_mul_f32 v[182:183], v[182:183], s[0:1] op_sel_hi:[1,0]
	v_pk_fma_f32 v[4:5], v[4:5], v[132:133], v[184:185]
	v_pk_fma_f32 v[2:3], v[2:3], v[130:131], v[182:183]
	global_load_dwordx4 v[182:185], v[152:153], off offset:512
	v_cndmask_b32_e32 v161, v220, v161, vcc
	v_lshlrev_b32_e32 v169, 2, v161
	v_mov_b32_e32 v212, v67
	v_mov_b32_e32 v213, v68
	v_add_f32_e32 v208, v127, v126
	v_add_f32_e32 v209, v128, v129
	s_waitcnt vmcnt(10)
	v_pk_mul_f32 v[228:229], v[228:229], s[0:1] op_sel_hi:[1,0]
	v_pk_mul_f32 v[226:227], v[226:227], s[0:1] op_sel_hi:[1,0]
	v_pk_fma_f32 v[124:125], v[124:125], v[136:137], v[228:229]
	v_pk_fma_f32 v[122:123], v[122:123], v[134:135], v[226:227]
	global_load_dwordx4 v[226:229], v[152:153], off offset:576
	s_waitcnt vmcnt(10)
	v_pk_mul_f32 v[232:233], v[232:233], s[0:1] op_sel_hi:[1,0]
	v_pk_mul_f32 v[230:231], v[230:231], s[0:1] op_sel_hi:[1,0]
	v_pk_fma_f32 v[72:73], v[72:73], v[144:145], v[232:233]
	v_pk_fma_f32 v[70:71], v[70:71], v[142:143], v[230:231]
	v_add_u32_e32 v154, 0x80, v160
	v_ashrrev_i32_e32 v155, 31, v154
	v_lshlrev_b64 v[154:155], 12, v[154:155]
	v_lshl_add_u64 v[154:155], s[44:45], 0, v[154:155]
	v_lshl_add_u64 v[154:155], v[154:155], 0, v[164:165]
	global_load_dwordx4 v[230:233], v[154:155], off
	s_waitcnt vmcnt(10)
	v_pk_mul_f32 v[236:237], v[236:237], s[0:1] op_sel_hi:[1,0]
	v_pk_mul_f32 v[234:235], v[234:235], s[0:1] op_sel_hi:[1,0]
	v_pk_fma_f32 v[40:41], v[40:41], v[140:141], v[236:237]
	v_pk_fma_f32 v[38:39], v[38:39], v[138:139], v[234:235]
	global_load_dwordx4 v[234:237], v[154:155], off offset:64
	s_waitcnt vmcnt(10)
	v_pk_mul_f32 v[240:241], v[240:241], s[0:1] op_sel_hi:[1,0]
	v_pk_mul_f32 v[238:239], v[238:239], s[0:1] op_sel_hi:[1,0]
	v_pk_fma_f32 v[8:9], v[8:9], v[132:133], v[240:241]
	v_pk_fma_f32 v[6:7], v[6:7], v[130:131], v[238:239]
	global_load_dwordx4 v[238:241], v[154:155], off offset:512
	s_waitcnt vmcnt(10)
	v_pk_mul_f32 v[244:245], v[244:245], s[0:1] op_sel_hi:[1,0]
	v_pk_mul_f32 v[242:243], v[242:243], s[0:1] op_sel_hi:[1,0]
	v_pk_fma_f32 v[120:121], v[120:121], v[136:137], v[244:245]
	v_pk_fma_f32 v[118:119], v[118:119], v[134:135], v[242:243]
	global_load_dwordx4 v[242:245], v[154:155], off offset:576
	s_waitcnt vmcnt(10)
	v_pk_mul_f32 v[202:203], v[202:203], s[0:1] op_sel_hi:[1,0]
	v_pk_mul_f32 v[200:201], v[200:201], s[0:1] op_sel_hi:[1,0]
	v_pk_fma_f32 v[76:77], v[76:77], v[144:145], v[202:203]
	v_pk_fma_f32 v[74:75], v[74:75], v[142:143], v[200:201]
	v_add_u32_e32 v156, 0x90, v160
	v_ashrrev_i32_e32 v157, 31, v156
	v_lshlrev_b64 v[156:157], 12, v[156:157]
	v_lshl_add_u64 v[156:157], s[44:45], 0, v[156:157]
	v_lshl_add_u64 v[156:157], v[156:157], 0, v[164:165]
	global_load_dwordx4 v[200:203], v[156:157], off
	s_waitcnt vmcnt(10)
	v_pk_mul_f32 v[206:207], v[206:207], s[0:1] op_sel_hi:[1,0]
	v_pk_mul_f32 v[204:205], v[204:205], s[0:1] op_sel_hi:[1,0]
	v_pk_fma_f32 v[44:45], v[44:45], v[140:141], v[206:207]
	v_pk_fma_f32 v[42:43], v[42:43], v[138:139], v[204:205]
	global_load_dwordx4 v[204:207], v[156:157], off offset:64
	s_waitcnt vmcnt(10)
	v_pk_mul_f32 v[172:173], v[172:173], s[0:1] op_sel_hi:[1,0]
	v_pk_mul_f32 v[170:171], v[170:171], s[0:1] op_sel_hi:[1,0]
	v_pk_fma_f32 v[12:13], v[12:13], v[132:133], v[172:173]
	v_pk_fma_f32 v[10:11], v[10:11], v[130:131], v[170:171]
	global_load_dwordx4 v[170:173], v[156:157], off offset:512
	s_waitcnt vmcnt(10)
	v_pk_mul_f32 v[176:177], v[176:177], s[0:1] op_sel_hi:[1,0]
	v_pk_mul_f32 v[174:175], v[174:175], s[0:1] op_sel_hi:[1,0]
	v_pk_fma_f32 v[116:117], v[116:117], v[136:137], v[176:177]
	v_pk_fma_f32 v[114:115], v[114:115], v[134:135], v[174:175]
	global_load_dwordx4 v[174:177], v[156:157], off offset:576
	s_waitcnt vmcnt(10)
	v_pk_mul_f32 v[180:181], v[180:181], s[0:1] op_sel_hi:[1,0]
	v_pk_mul_f32 v[178:179], v[178:179], s[0:1] op_sel_hi:[1,0]
	v_pk_fma_f32 v[80:81], v[80:81], v[144:145], v[180:181]
	v_pk_fma_f32 v[78:79], v[78:79], v[142:143], v[178:179]
	v_add_u32_e32 v158, 0xa0, v160
	v_ashrrev_i32_e32 v159, 31, v158
	v_lshlrev_b64 v[158:159], 12, v[158:159]
	v_lshl_add_u64 v[158:159], s[44:45], 0, v[158:159]
	v_lshl_add_u64 v[158:159], v[158:159], 0, v[164:165]
	global_load_dwordx4 v[178:181], v[158:159], off
	s_waitcnt vmcnt(10)
	v_pk_mul_f32 v[184:185], v[184:185], s[0:1] op_sel_hi:[1,0]
	v_pk_mul_f32 v[182:183], v[182:183], s[0:1] op_sel_hi:[1,0]
	v_pk_fma_f32 v[48:49], v[48:49], v[140:141], v[184:185]
	v_pk_fma_f32 v[46:47], v[46:47], v[138:139], v[182:183]
	global_load_dwordx4 v[182:185], v[158:159], off offset:64
	s_waitcnt vmcnt(10)
	v_pk_mul_f32 v[228:229], v[228:229], s[0:1] op_sel_hi:[1,0]
	v_pk_mul_f32 v[226:227], v[226:227], s[0:1] op_sel_hi:[1,0]
	v_pk_fma_f32 v[16:17], v[16:17], v[132:133], v[228:229]
	v_pk_fma_f32 v[14:15], v[14:15], v[130:131], v[226:227]
	global_load_dwordx4 v[226:229], v[158:159], off offset:512
	s_waitcnt vmcnt(10)
	v_pk_mul_f32 v[232:233], v[232:233], s[0:1] op_sel_hi:[1,0]
	v_pk_mul_f32 v[230:231], v[230:231], s[0:1] op_sel_hi:[1,0]
	v_pk_fma_f32 v[108:109], v[108:109], v[136:137], v[232:233]
	v_pk_fma_f32 v[106:107], v[106:107], v[134:135], v[230:231]
	global_load_dwordx4 v[230:233], v[158:159], off offset:576
	s_waitcnt vmcnt(10)
	v_pk_mul_f32 v[236:237], v[236:237], s[0:1] op_sel_hi:[1,0]
	v_pk_mul_f32 v[234:235], v[234:235], s[0:1] op_sel_hi:[1,0]
	v_pk_fma_f32 v[84:85], v[84:85], v[144:145], v[236:237]
	v_pk_fma_f32 v[82:83], v[82:83], v[142:143], v[234:235]
	s_waitcnt vmcnt(9)
	v_pk_mul_f32 v[240:241], v[240:241], s[0:1] op_sel_hi:[1,0]
	v_pk_mul_f32 v[238:239], v[238:239], s[0:1] op_sel_hi:[1,0]
	v_pk_fma_f32 v[52:53], v[52:53], v[140:141], v[240:241]
	v_pk_fma_f32 v[50:51], v[50:51], v[138:139], v[238:239]
	s_waitcnt vmcnt(8)
	v_pk_mul_f32 v[244:245], v[244:245], s[0:1] op_sel_hi:[1,0]
	v_pk_mul_f32 v[242:243], v[242:243], s[0:1] op_sel_hi:[1,0]
	v_pk_fma_f32 v[20:21], v[20:21], v[132:133], v[244:245]
	v_pk_fma_f32 v[18:19], v[18:19], v[130:131], v[242:243]
	s_waitcnt vmcnt(7)
	v_pk_mul_f32 v[202:203], v[202:203], s[0:1] op_sel_hi:[1,0]
	v_pk_mul_f32 v[200:201], v[200:201], s[0:1] op_sel_hi:[1,0]
	v_pk_fma_f32 v[112:113], v[112:113], v[136:137], v[202:203]
	v_pk_fma_f32 v[110:111], v[110:111], v[134:135], v[200:201]
	s_waitcnt vmcnt(6)
	v_pk_mul_f32 v[206:207], v[206:207], s[0:1] op_sel_hi:[1,0]
	v_pk_mul_f32 v[204:205], v[204:205], s[0:1] op_sel_hi:[1,0]
	v_pk_fma_f32 v[88:89], v[88:89], v[144:145], v[206:207]
	v_pk_fma_f32 v[86:87], v[86:87], v[142:143], v[204:205]
	s_waitcnt vmcnt(5)
	v_pk_mul_f32 v[172:173], v[172:173], s[0:1] op_sel_hi:[1,0]
	v_pk_mul_f32 v[170:171], v[170:171], s[0:1] op_sel_hi:[1,0]
	v_pk_fma_f32 v[56:57], v[56:57], v[140:141], v[172:173]
	v_pk_fma_f32 v[54:55], v[54:55], v[138:139], v[170:171]
	s_waitcnt vmcnt(4)
	v_pk_mul_f32 v[176:177], v[176:177], s[0:1] op_sel_hi:[1,0]
	v_pk_mul_f32 v[174:175], v[174:175], s[0:1] op_sel_hi:[1,0]
	v_pk_fma_f32 v[24:25], v[24:25], v[132:133], v[176:177]
	v_pk_fma_f32 v[22:23], v[22:23], v[130:131], v[174:175]
	s_waitcnt vmcnt(3)
	v_pk_mul_f32 v[180:181], v[180:181], s[0:1] op_sel_hi:[1,0]
	v_pk_mul_f32 v[178:179], v[178:179], s[0:1] op_sel_hi:[1,0]
	v_pk_fma_f32 v[104:105], v[104:105], v[136:137], v[180:181]
	v_pk_fma_f32 v[102:103], v[102:103], v[134:135], v[178:179]
	s_waitcnt vmcnt(2)
	v_pk_mul_f32 v[184:185], v[184:185], s[0:1] op_sel_hi:[1,0]
	v_pk_mul_f32 v[182:183], v[182:183], s[0:1] op_sel_hi:[1,0]
	v_pk_fma_f32 v[92:93], v[92:93], v[144:145], v[184:185]
	v_pk_fma_f32 v[90:91], v[90:91], v[142:143], v[182:183]
	s_waitcnt vmcnt(1)
	v_pk_mul_f32 v[228:229], v[228:229], s[0:1] op_sel_hi:[1,0]
	v_pk_mul_f32 v[226:227], v[226:227], s[0:1] op_sel_hi:[1,0]
	v_pk_fma_f32 v[60:61], v[60:61], v[140:141], v[228:229]
	v_pk_fma_f32 v[58:59], v[58:59], v[138:139], v[226:227]
	s_waitcnt vmcnt(0)
	v_pk_mul_f32 v[232:233], v[232:233], s[0:1] op_sel_hi:[1,0]
	v_pk_mul_f32 v[230:231], v[230:231], s[0:1] op_sel_hi:[1,0]
	v_pk_fma_f32 v[28:29], v[28:29], v[132:133], v[232:233]
	v_pk_fma_f32 v[26:27], v[26:27], v[130:131], v[230:231]
	v_add_u32_e32 v160, 0xb0, v160
	v_ashrrev_i32_e32 v161, 31, v160
	v_lshlrev_b64 v[160:161], 12, v[160:161]
	v_lshl_add_u64 v[160:161], s[44:45], 0, v[160:161]
	v_lshl_add_u64 v[160:161], v[160:161], 0, v[164:165]
	global_load_dwordx4 v[176:179], v[160:161], off
	global_load_dwordx4 v[180:183], v[160:161], off offset:64
	global_load_dwordx4 v[200:203], v[160:161], off offset:512
	global_load_dwordx4 v[204:207], v[160:161], off offset:576
	v_add_f32_e32 v173, v34, v35
	v_add_f32_e32 v175, v36, v37
	v_mov_b32_e32 v172, v2
	v_mov_b32_e32 v174, v3
	v_add_f32_e32 v170, v212, v66
	v_add_f32_e32 v171, v213, v69
	v_pk_add_f32 v[172:173], v[172:173], v[174:175]
	v_add_f32_e32 v174, v208, v209
	v_pk_add_f32 v[170:171], v[170:171], v[170:171] op_sel_hi:[0,1]
	v_mov_b32_e32 v184, v5
	v_add_f32_e32 v185, 0, v174
	v_mov_b32_e32 v170, v4
	v_pk_add_f32 v[170:171], v[170:171], v[184:185]
	s_waitcnt vmcnt(3)
	v_pk_mul_f32 v[178:179], v[178:179], s[0:1] op_sel_hi:[1,0]
	v_pk_add_f32 v[170:171], v[172:173], v[170:171]
	v_pk_mul_f32 v[176:177], v[176:177], s[0:1] op_sel_hi:[1,0]
	v_add_f32_e32 v170, v170, v171
	ds_bpermute_b32 v172, v169, v170
	v_xor_b32_e32 v171, 32, v220
	v_cmp_lt_i32_e32 vcc, v171, v188
	s_waitcnt vmcnt(2)
	v_pk_mul_f32 v[182:183], v[182:183], s[0:1] op_sel_hi:[1,0]
	v_pk_mul_f32 v[180:181], v[180:181], s[0:1] op_sel_hi:[1,0]
	v_cndmask_b32_e32 v171, v220, v171, vcc
	v_lshlrev_b32_e32 v171, 2, v171
	s_waitcnt lgkmcnt(0)
	v_add_f32_e32 v170, v170, v172
	ds_bpermute_b32 v172, v171, v170
	s_waitcnt vmcnt(1)
	v_pk_mul_f32 v[200:201], v[200:201], s[0:1] op_sel_hi:[1,0]
	s_waitcnt vmcnt(0)
	v_pk_mul_f32 v[204:205], v[204:205], s[0:1] op_sel_hi:[1,0]
	v_pk_fma_f32 v[100:101], v[100:101], v[136:137], v[178:179]
	v_pk_fma_f32 v[98:99], v[98:99], v[134:135], v[176:177]
	s_waitcnt lgkmcnt(0)
	v_add_f32_e32 v172, v170, v172
	v_fmamk_f32 v173, v172, 0xbc800000, v129
	v_fmamk_f32 v175, v172, 0xbc800000, v127
	v_fmamk_f32 v185, v172, 0xbc800000, v69
	v_fmamk_f32 v208, v172, 0xbc800000, v67
	v_fmamk_f32 v170, v172, 0xbc800000, v128
	v_fmamk_f32 v174, v172, 0xbc800000, v126
	v_fmamk_f32 v184, v172, 0xbc800000, v68
	v_fmamk_f32 v188, v172, 0xbc800000, v66
	v_fmamk_f32 v210, v172, 0xbc800000, v37
	v_fmamk_f32 v212, v172, 0xbc800000, v35
	v_mul_f32_e32 v175, v175, v175
	v_mul_f32_e32 v173, v173, v173
	v_mul_f32_e32 v208, v208, v208
	v_mul_f32_e32 v185, v185, v185
	v_fmamk_f32 v209, v172, 0xbc800000, v36
	v_fmamk_f32 v211, v172, 0xbc800000, v34
	v_fmamk_f32 v214, v172, 0xbc800000, v5
	v_fmamk_f32 v216, v172, 0xbc800000, v3
	v_mul_f32_e32 v212, v212, v212
	v_mul_f32_e32 v210, v210, v210
	v_fmac_f32_e32 v175, v174, v174
	v_fmac_f32_e32 v173, v170, v170
	v_fmac_f32_e32 v208, v188, v188
	v_fmac_f32_e32 v185, v184, v184
	v_fmamk_f32 v213, v172, 0xbc800000, v4
	v_fmamk_f32 v215, v172, 0xbc800000, v2
	v_mul_f32_e32 v216, v216, v216
	v_mul_f32_e32 v214, v214, v214
	v_fmac_f32_e32 v212, v211, v211
	v_fmac_f32_e32 v210, v209, v209
	v_add_f32_e32 v170, v175, v173
	v_add_f32_e32 v173, v208, v185
	v_fmac_f32_e32 v216, v215, v215
	v_fmac_f32_e32 v214, v213, v213
	v_add_f32_e32 v174, v212, v210
	v_add_f32_e32 v170, v170, v173
	v_add_f32_e32 v175, v216, v214
	v_add_f32_e32 v170, v174, v170
	v_add_f32_e32 v173, v175, v170
	ds_bpermute_b32 v174, v169, v173
	v_pk_mul_f32 v[184:185], v[202:203], s[0:1] op_sel_hi:[1,0]
	v_pk_mul_f32 v[202:203], v[206:207], s[0:1] op_sel_hi:[1,0]
	v_pk_fma_f32 v[96:97], v[96:97], v[144:145], v[182:183]
	v_pk_fma_f32 v[94:95], v[94:95], v[142:143], v[180:181]
	s_waitcnt lgkmcnt(0)
	v_add_f32_e32 v173, v173, v174
	ds_bpermute_b32 v174, v171, v173
	v_pk_fma_f32 v[64:65], v[64:65], v[140:141], v[184:185]
	v_pk_fma_f32 v[62:63], v[62:63], v[138:139], v[200:201]
	v_pk_fma_f32 v[32:33], v[32:33], v[132:133], v[202:203]
	v_pk_fma_f32 v[30:31], v[30:31], v[130:131], v[204:205]
	v_and_b32_e32 v170, 63, v167
	s_lshl_b32 s0, s18, 3
	v_cmp_gt_u32_e32 vcc, 16, v170
	s_add_i32 s8, s0, 0
	s_and_saveexec_b64 s[0:1], vcc
	s_cbranch_execz .LBB0_3246
	s_lshl_b32 s9, s17, 11
	s_add_i32 s9, s8, s9
	v_mul_f32_e32 v130, 0x3c800000, v172
	v_lshl_add_u32 v132, v168, 5, s9
	s_waitcnt lgkmcnt(0)
	v_add_f32_e32 v131, v173, v174
	ds_write_b64 v132, v[130:131]
.LBB0_3246:
	s_or_b64 exec, exec, s[0:1]
	v_add_f32_e32 v130, v123, v122
	v_add_f32_e32 v131, v124, v125
	v_add_f32_e32 v132, v71, v70
	v_add_f32_e32 v133, v72, v73
	v_add_f32_e32 v130, v130, v131
	v_pk_add_f32 v[132:133], v[132:133], v[132:133] op_sel_hi:[0,1]
	v_add_f32_e32 v131, 0, v130
	v_add_f32_e32 v135, v38, v39
	v_add_f32_e32 v137, v40, v41
	v_mov_b32_e32 v134, v6
	v_mov_b32_e32 v136, v7
	v_mov_b32_e32 v132, v8
	v_mov_b32_e32 v130, v9
	v_pk_add_f32 v[134:135], v[134:135], v[136:137]
	v_pk_add_f32 v[130:131], v[132:133], v[130:131]
	s_nop 0
	v_pk_add_f32 v[130:131], v[134:135], v[130:131]
	s_nop 0
	v_add_f32_e32 v130, v130, v131
	ds_bpermute_b32 v131, v169, v130
	s_waitcnt lgkmcnt(0)
	v_add_f32_e32 v130, v130, v131
	ds_bpermute_b32 v131, v171, v130
	s_waitcnt lgkmcnt(0)
	v_add_f32_e32 v130, v130, v131
	v_fmamk_f32 v132, v130, 0xbc800000, v125
	v_fmamk_f32 v134, v130, 0xbc800000, v123
	v_fmamk_f32 v131, v130, 0xbc800000, v124
	v_fmamk_f32 v133, v130, 0xbc800000, v122
	v_mul_f32_e32 v134, v134, v134
	v_mul_f32_e32 v132, v132, v132
	v_fmac_f32_e32 v134, v133, v133
	v_fmac_f32_e32 v132, v131, v131
	v_fmamk_f32 v133, v130, 0xbc800000, v73
	v_fmamk_f32 v135, v130, 0xbc800000, v71
	v_add_f32_e32 v131, v134, v132
	v_fmamk_f32 v132, v130, 0xbc800000, v72
	v_fmamk_f32 v134, v130, 0xbc800000, v70
	v_mul_f32_e32 v135, v135, v135
	v_mul_f32_e32 v133, v133, v133
	v_fmac_f32_e32 v135, v134, v134
	v_fmac_f32_e32 v133, v132, v132
	v_add_f32_e32 v132, v135, v133
	v_fmamk_f32 v133, v130, 0xbc800000, v41
	v_fmamk_f32 v135, v130, 0xbc800000, v39
	v_add_f32_e32 v131, v131, v132
	v_fmamk_f32 v132, v130, 0xbc800000, v40
	v_fmamk_f32 v134, v130, 0xbc800000, v38
	v_mul_f32_e32 v135, v135, v135
	v_mul_f32_e32 v133, v133, v133
	v_fmac_f32_e32 v135, v134, v134
	v_fmac_f32_e32 v133, v132, v132
	v_add_f32_e32 v132, v135, v133
	v_fmamk_f32 v133, v130, 0xbc800000, v9
	v_fmamk_f32 v135, v130, 0xbc800000, v7
	v_add_f32_e32 v131, v132, v131
	v_fmamk_f32 v132, v130, 0xbc800000, v8
	v_fmamk_f32 v134, v130, 0xbc800000, v6
	v_mul_f32_e32 v135, v135, v135
	v_mul_f32_e32 v133, v133, v133
	v_fmac_f32_e32 v135, v134, v134
	v_fmac_f32_e32 v133, v132, v132
	v_add_f32_e32 v132, v135, v133
	v_add_f32_e32 v131, v132, v131
	ds_bpermute_b32 v132, v169, v131
	s_waitcnt lgkmcnt(0)
	v_add_f32_e32 v131, v131, v132
	ds_bpermute_b32 v132, v171, v131
	s_and_saveexec_b64 s[0:1], vcc
	s_cbranch_execz .LBB0_3248
	s_lshl_b32 s9, s17, 11
	s_add_i32 s9, s8, s9
	v_mul_f32_e32 v130, 0x3c800000, v130
	v_lshl_add_u32 v133, v168, 5, s9
	s_waitcnt lgkmcnt(0)
	v_add_f32_e32 v131, v131, v132
	ds_write_b64 v133, v[130:131] offset:512
.LBB0_3248:
	s_or_b64 exec, exec, s[0:1]
	s_waitcnt lgkmcnt(0)
	v_add_f32_e32 v130, v119, v118
	v_add_f32_e32 v131, v120, v121
	v_add_f32_e32 v132, v75, v74
	v_add_f32_e32 v133, v76, v77
	v_add_f32_e32 v130, v130, v131
	v_pk_add_f32 v[132:133], v[132:133], v[132:133] op_sel_hi:[0,1]
	v_add_f32_e32 v131, 0, v130
	v_add_f32_e32 v135, v42, v43
	v_add_f32_e32 v137, v44, v45
	v_mov_b32_e32 v134, v10
	v_mov_b32_e32 v136, v11
	v_mov_b32_e32 v132, v12
	v_mov_b32_e32 v130, v13
	v_pk_add_f32 v[134:135], v[134:135], v[136:137]
	v_pk_add_f32 v[130:131], v[132:133], v[130:131]
	s_nop 0
	v_pk_add_f32 v[130:131], v[134:135], v[130:131]
	s_nop 0
	v_add_f32_e32 v130, v130, v131
	ds_bpermute_b32 v131, v169, v130
	s_waitcnt lgkmcnt(0)
	v_add_f32_e32 v130, v130, v131
	ds_bpermute_b32 v131, v171, v130
	s_waitcnt lgkmcnt(0)
	v_add_f32_e32 v130, v130, v131
	v_fmamk_f32 v132, v130, 0xbc800000, v121
	v_fmamk_f32 v134, v130, 0xbc800000, v119
	v_fmamk_f32 v131, v130, 0xbc800000, v120
	v_fmamk_f32 v133, v130, 0xbc800000, v118
	v_mul_f32_e32 v134, v134, v134
	v_mul_f32_e32 v132, v132, v132
	v_fmac_f32_e32 v134, v133, v133
	v_fmac_f32_e32 v132, v131, v131
	v_fmamk_f32 v133, v130, 0xbc800000, v77
	v_fmamk_f32 v135, v130, 0xbc800000, v75
	v_add_f32_e32 v131, v134, v132
	v_fmamk_f32 v132, v130, 0xbc800000, v76
	v_fmamk_f32 v134, v130, 0xbc800000, v74
	v_mul_f32_e32 v135, v135, v135
	v_mul_f32_e32 v133, v133, v133
	v_fmac_f32_e32 v135, v134, v134
	v_fmac_f32_e32 v133, v132, v132
	v_add_f32_e32 v132, v135, v133
	v_fmamk_f32 v133, v130, 0xbc800000, v45
	v_fmamk_f32 v135, v130, 0xbc800000, v43
	v_add_f32_e32 v131, v131, v132
	v_fmamk_f32 v132, v130, 0xbc800000, v44
	v_fmamk_f32 v134, v130, 0xbc800000, v42
	v_mul_f32_e32 v135, v135, v135
	v_mul_f32_e32 v133, v133, v133
	v_fmac_f32_e32 v135, v134, v134
	v_fmac_f32_e32 v133, v132, v132
	v_add_f32_e32 v132, v135, v133
	v_fmamk_f32 v133, v130, 0xbc800000, v13
	v_fmamk_f32 v135, v130, 0xbc800000, v11
	v_add_f32_e32 v131, v132, v131
	v_fmamk_f32 v132, v130, 0xbc800000, v12
	v_fmamk_f32 v134, v130, 0xbc800000, v10
	v_mul_f32_e32 v135, v135, v135
	v_mul_f32_e32 v133, v133, v133
	v_fmac_f32_e32 v135, v134, v134
	v_fmac_f32_e32 v133, v132, v132
	v_add_f32_e32 v132, v135, v133
	v_add_f32_e32 v131, v132, v131
	ds_bpermute_b32 v132, v169, v131
	s_waitcnt lgkmcnt(0)
	v_add_f32_e32 v131, v131, v132
	ds_bpermute_b32 v132, v171, v131
	s_and_saveexec_b64 s[0:1], vcc
	s_cbranch_execz .LBB0_3250
	s_lshl_b32 s9, s17, 11
	s_add_i32 s9, s8, s9
	v_mul_f32_e32 v130, 0x3c800000, v130
	v_lshl_add_u32 v133, v168, 5, s9
	s_waitcnt lgkmcnt(0)
	v_add_f32_e32 v131, v131, v132
	ds_write_b64 v133, v[130:131] offset:1024
.LBB0_3250:
	s_or_b64 exec, exec, s[0:1]
	s_waitcnt lgkmcnt(0)
	v_add_f32_e32 v130, v115, v114
	v_add_f32_e32 v131, v116, v117
	v_add_f32_e32 v132, v79, v78
	v_add_f32_e32 v133, v80, v81
	v_add_f32_e32 v130, v130, v131
	v_pk_add_f32 v[132:133], v[132:133], v[132:133] op_sel_hi:[0,1]
	v_add_f32_e32 v131, 0, v130
	v_add_f32_e32 v135, v46, v47
	v_add_f32_e32 v137, v48, v49
	v_mov_b32_e32 v134, v14
	v_mov_b32_e32 v136, v15
	v_mov_b32_e32 v132, v16
	v_mov_b32_e32 v130, v17
	v_pk_add_f32 v[134:135], v[134:135], v[136:137]
	v_pk_add_f32 v[130:131], v[132:133], v[130:131]
	s_nop 0
	v_pk_add_f32 v[130:131], v[134:135], v[130:131]
	s_nop 0
	v_add_f32_e32 v130, v130, v131
	ds_bpermute_b32 v131, v169, v130
	s_waitcnt lgkmcnt(0)
	v_add_f32_e32 v130, v130, v131
	ds_bpermute_b32 v131, v171, v130
	s_waitcnt lgkmcnt(0)
	v_add_f32_e32 v130, v130, v131
	v_fmamk_f32 v132, v130, 0xbc800000, v117
	v_fmamk_f32 v134, v130, 0xbc800000, v115
	v_fmamk_f32 v131, v130, 0xbc800000, v116
	v_fmamk_f32 v133, v130, 0xbc800000, v114
	v_mul_f32_e32 v134, v134, v134
	v_mul_f32_e32 v132, v132, v132
	v_fmac_f32_e32 v134, v133, v133
	v_fmac_f32_e32 v132, v131, v131
	v_fmamk_f32 v133, v130, 0xbc800000, v81
	v_fmamk_f32 v135, v130, 0xbc800000, v79
	v_add_f32_e32 v131, v134, v132
	v_fmamk_f32 v132, v130, 0xbc800000, v80
	v_fmamk_f32 v134, v130, 0xbc800000, v78
	v_mul_f32_e32 v135, v135, v135
	v_mul_f32_e32 v133, v133, v133
	v_fmac_f32_e32 v135, v134, v134
	v_fmac_f32_e32 v133, v132, v132
	v_add_f32_e32 v132, v135, v133
	v_fmamk_f32 v133, v130, 0xbc800000, v49
	v_fmamk_f32 v135, v130, 0xbc800000, v47
	v_add_f32_e32 v131, v131, v132
	v_fmamk_f32 v132, v130, 0xbc800000, v48
	v_fmamk_f32 v134, v130, 0xbc800000, v46
	v_mul_f32_e32 v135, v135, v135
	v_mul_f32_e32 v133, v133, v133
	v_fmac_f32_e32 v135, v134, v134
	v_fmac_f32_e32 v133, v132, v132
	v_add_f32_e32 v132, v135, v133
	v_fmamk_f32 v133, v130, 0xbc800000, v17
	v_fmamk_f32 v135, v130, 0xbc800000, v15
	v_add_f32_e32 v131, v132, v131
	v_fmamk_f32 v132, v130, 0xbc800000, v16
	v_fmamk_f32 v134, v130, 0xbc800000, v14
	v_mul_f32_e32 v135, v135, v135
	v_mul_f32_e32 v133, v133, v133
	v_fmac_f32_e32 v135, v134, v134
	v_fmac_f32_e32 v133, v132, v132
	v_add_f32_e32 v132, v135, v133
	v_add_f32_e32 v131, v132, v131
	ds_bpermute_b32 v132, v169, v131
	s_waitcnt lgkmcnt(0)
	v_add_f32_e32 v131, v131, v132
	ds_bpermute_b32 v132, v171, v131
	s_and_saveexec_b64 s[0:1], vcc
	s_cbranch_execz .LBB0_3252
	s_lshl_b32 s9, s17, 11
	s_add_i32 s9, s8, s9
	v_mul_f32_e32 v130, 0x3c800000, v130
	v_lshl_add_u32 v133, v168, 5, s9
	s_waitcnt lgkmcnt(0)
	v_add_f32_e32 v131, v131, v132
	ds_write_b64 v133, v[130:131] offset:1536
.LBB0_3252:
	s_or_b64 exec, exec, s[0:1]
	s_waitcnt lgkmcnt(0)
	v_add_f32_e32 v130, v107, v106
	v_add_f32_e32 v131, v108, v109
	v_add_f32_e32 v132, v83, v82
	v_add_f32_e32 v133, v84, v85
	v_add_f32_e32 v130, v130, v131
	v_pk_add_f32 v[132:133], v[132:133], v[132:133] op_sel_hi:[0,1]
	v_add_f32_e32 v131, 0, v130
	v_add_f32_e32 v135, v50, v51
	v_add_f32_e32 v137, v52, v53
	v_mov_b32_e32 v134, v18
	v_mov_b32_e32 v136, v19
	v_mov_b32_e32 v132, v20
	v_mov_b32_e32 v130, v21
	v_pk_add_f32 v[134:135], v[134:135], v[136:137]
	v_pk_add_f32 v[130:131], v[132:133], v[130:131]
	s_nop 0
	v_pk_add_f32 v[130:131], v[134:135], v[130:131]
	s_nop 0
	v_add_f32_e32 v130, v130, v131
	ds_bpermute_b32 v131, v169, v130
	s_waitcnt lgkmcnt(0)
	v_add_f32_e32 v130, v130, v131
	ds_bpermute_b32 v131, v171, v130
	s_waitcnt lgkmcnt(0)
	v_add_f32_e32 v130, v130, v131
	v_fmamk_f32 v132, v130, 0xbc800000, v109
	v_fmamk_f32 v134, v130, 0xbc800000, v107
	v_fmamk_f32 v131, v130, 0xbc800000, v108
	v_fmamk_f32 v133, v130, 0xbc800000, v106
	v_mul_f32_e32 v134, v134, v134
	v_mul_f32_e32 v132, v132, v132
	v_fmac_f32_e32 v134, v133, v133
	v_fmac_f32_e32 v132, v131, v131
	v_fmamk_f32 v133, v130, 0xbc800000, v85
	v_fmamk_f32 v135, v130, 0xbc800000, v83
	v_add_f32_e32 v131, v134, v132
	v_fmamk_f32 v132, v130, 0xbc800000, v84
	v_fmamk_f32 v134, v130, 0xbc800000, v82
	v_mul_f32_e32 v135, v135, v135
	v_mul_f32_e32 v133, v133, v133
	v_fmac_f32_e32 v135, v134, v134
	v_fmac_f32_e32 v133, v132, v132
	v_add_f32_e32 v132, v135, v133
	v_fmamk_f32 v133, v130, 0xbc800000, v53
	v_fmamk_f32 v135, v130, 0xbc800000, v51
	v_add_f32_e32 v131, v131, v132
	v_fmamk_f32 v132, v130, 0xbc800000, v52
	v_fmamk_f32 v134, v130, 0xbc800000, v50
	v_mul_f32_e32 v135, v135, v135
	v_mul_f32_e32 v133, v133, v133
	v_fmac_f32_e32 v135, v134, v134
	v_fmac_f32_e32 v133, v132, v132
	v_add_f32_e32 v132, v135, v133
	v_fmamk_f32 v133, v130, 0xbc800000, v21
	v_fmamk_f32 v135, v130, 0xbc800000, v19
	v_add_f32_e32 v131, v132, v131
	v_fmamk_f32 v132, v130, 0xbc800000, v20
	v_fmamk_f32 v134, v130, 0xbc800000, v18
	v_mul_f32_e32 v135, v135, v135
	v_mul_f32_e32 v133, v133, v133
	v_fmac_f32_e32 v135, v134, v134
	v_fmac_f32_e32 v133, v132, v132
	v_add_f32_e32 v132, v135, v133
	v_add_f32_e32 v131, v132, v131
	ds_bpermute_b32 v132, v169, v131
	s_waitcnt lgkmcnt(0)
	v_add_f32_e32 v131, v131, v132
	ds_bpermute_b32 v132, v171, v131
	s_and_saveexec_b64 s[0:1], vcc
	s_cbranch_execz .LBB0_3254
	s_lshl_b32 s9, s17, 11
	s_add_i32 s9, s8, s9
	v_mul_f32_e32 v130, 0x3c800000, v130
	v_lshl_add_u32 v133, v168, 5, s9
	s_waitcnt lgkmcnt(0)
	v_add_f32_e32 v131, v131, v132
	ds_write_b64 v133, v[130:131] offset:4096
.LBB0_3254:
	s_or_b64 exec, exec, s[0:1]
	s_waitcnt lgkmcnt(0)
	v_add_f32_e32 v130, v111, v110
	v_add_f32_e32 v131, v112, v113
	v_add_f32_e32 v132, v87, v86
	v_add_f32_e32 v133, v88, v89
	v_add_f32_e32 v130, v130, v131
	v_pk_add_f32 v[132:133], v[132:133], v[132:133] op_sel_hi:[0,1]
	v_add_f32_e32 v131, 0, v130
	v_add_f32_e32 v135, v54, v55
	v_add_f32_e32 v137, v56, v57
	v_mov_b32_e32 v134, v22
	v_mov_b32_e32 v136, v23
	v_mov_b32_e32 v132, v24
	v_mov_b32_e32 v130, v25
	v_pk_add_f32 v[134:135], v[134:135], v[136:137]
	v_pk_add_f32 v[130:131], v[132:133], v[130:131]
	s_nop 0
	v_pk_add_f32 v[130:131], v[134:135], v[130:131]
	s_nop 0
	v_add_f32_e32 v130, v130, v131
	ds_bpermute_b32 v131, v169, v130
	s_waitcnt lgkmcnt(0)
	v_add_f32_e32 v130, v130, v131
	ds_bpermute_b32 v131, v171, v130
	s_waitcnt lgkmcnt(0)
	v_add_f32_e32 v130, v130, v131
	v_fmamk_f32 v132, v130, 0xbc800000, v113
	v_fmamk_f32 v134, v130, 0xbc800000, v111
	v_fmamk_f32 v131, v130, 0xbc800000, v112
	v_fmamk_f32 v133, v130, 0xbc800000, v110
	v_mul_f32_e32 v134, v134, v134
	v_mul_f32_e32 v132, v132, v132
	v_fmac_f32_e32 v134, v133, v133
	v_fmac_f32_e32 v132, v131, v131
	v_fmamk_f32 v133, v130, 0xbc800000, v89
	v_fmamk_f32 v135, v130, 0xbc800000, v87
	v_add_f32_e32 v131, v134, v132
	v_fmamk_f32 v132, v130, 0xbc800000, v88
	v_fmamk_f32 v134, v130, 0xbc800000, v86
	v_mul_f32_e32 v135, v135, v135
	v_mul_f32_e32 v133, v133, v133
	v_fmac_f32_e32 v135, v134, v134
	v_fmac_f32_e32 v133, v132, v132
	v_add_f32_e32 v132, v135, v133
	v_fmamk_f32 v133, v130, 0xbc800000, v57
	v_fmamk_f32 v135, v130, 0xbc800000, v55
	v_add_f32_e32 v131, v131, v132
	v_fmamk_f32 v132, v130, 0xbc800000, v56
	v_fmamk_f32 v134, v130, 0xbc800000, v54
	v_mul_f32_e32 v135, v135, v135
	v_mul_f32_e32 v133, v133, v133
	v_fmac_f32_e32 v135, v134, v134
	v_fmac_f32_e32 v133, v132, v132
	v_add_f32_e32 v132, v135, v133
	v_fmamk_f32 v133, v130, 0xbc800000, v25
	v_fmamk_f32 v135, v130, 0xbc800000, v23
	v_add_f32_e32 v131, v132, v131
	v_fmamk_f32 v132, v130, 0xbc800000, v24
	v_fmamk_f32 v134, v130, 0xbc800000, v22
	v_mul_f32_e32 v135, v135, v135
	v_mul_f32_e32 v133, v133, v133
	v_fmac_f32_e32 v135, v134, v134
	v_fmac_f32_e32 v133, v132, v132
	v_add_f32_e32 v132, v135, v133
	v_add_f32_e32 v131, v132, v131
	ds_bpermute_b32 v132, v169, v131
	s_waitcnt lgkmcnt(0)
	v_add_f32_e32 v131, v131, v132
	ds_bpermute_b32 v132, v171, v131
	s_and_saveexec_b64 s[0:1], vcc
	s_cbranch_execz .LBB0_3256
	s_lshl_b32 s9, s17, 11
	s_add_i32 s9, s8, s9
	v_mul_f32_e32 v130, 0x3c800000, v130
	v_lshl_add_u32 v133, v168, 5, s9
	s_waitcnt lgkmcnt(0)
	v_add_f32_e32 v131, v131, v132
	ds_write_b64 v133, v[130:131] offset:4608
.LBB0_3256:
	s_or_b64 exec, exec, s[0:1]
	s_waitcnt lgkmcnt(0)
	v_add_f32_e32 v130, v103, v102
	v_add_f32_e32 v131, v104, v105
	v_add_f32_e32 v132, v91, v90
	v_add_f32_e32 v133, v92, v93
	v_add_f32_e32 v130, v130, v131
	v_pk_add_f32 v[132:133], v[132:133], v[132:133] op_sel_hi:[0,1]
	v_add_f32_e32 v131, 0, v130
	v_add_f32_e32 v135, v58, v59
	v_add_f32_e32 v137, v60, v61
	v_mov_b32_e32 v134, v26
	v_mov_b32_e32 v136, v27
	v_mov_b32_e32 v132, v28
	v_mov_b32_e32 v130, v29
	v_pk_add_f32 v[134:135], v[134:135], v[136:137]
	v_pk_add_f32 v[130:131], v[132:133], v[130:131]
	s_nop 0
	v_pk_add_f32 v[130:131], v[134:135], v[130:131]
	s_nop 0
	v_add_f32_e32 v130, v130, v131
	ds_bpermute_b32 v131, v169, v130
	s_waitcnt lgkmcnt(0)
	v_add_f32_e32 v130, v130, v131
	ds_bpermute_b32 v131, v171, v130
	s_waitcnt lgkmcnt(0)
	v_add_f32_e32 v130, v130, v131
	v_fmamk_f32 v132, v130, 0xbc800000, v105
	v_fmamk_f32 v134, v130, 0xbc800000, v103
	v_fmamk_f32 v131, v130, 0xbc800000, v104
	v_fmamk_f32 v133, v130, 0xbc800000, v102
	v_mul_f32_e32 v134, v134, v134
	v_mul_f32_e32 v132, v132, v132
	v_fmac_f32_e32 v134, v133, v133
	v_fmac_f32_e32 v132, v131, v131
	v_fmamk_f32 v133, v130, 0xbc800000, v93
	v_fmamk_f32 v135, v130, 0xbc800000, v91
	v_add_f32_e32 v131, v134, v132
	v_fmamk_f32 v132, v130, 0xbc800000, v92
	v_fmamk_f32 v134, v130, 0xbc800000, v90
	v_mul_f32_e32 v135, v135, v135
	v_mul_f32_e32 v133, v133, v133
	v_fmac_f32_e32 v135, v134, v134
	v_fmac_f32_e32 v133, v132, v132
	v_add_f32_e32 v132, v135, v133
	v_fmamk_f32 v133, v130, 0xbc800000, v61
	v_fmamk_f32 v135, v130, 0xbc800000, v59
	v_add_f32_e32 v131, v131, v132
	v_fmamk_f32 v132, v130, 0xbc800000, v60
	v_fmamk_f32 v134, v130, 0xbc800000, v58
	v_mul_f32_e32 v135, v135, v135
	v_mul_f32_e32 v133, v133, v133
	v_fmac_f32_e32 v135, v134, v134
	v_fmac_f32_e32 v133, v132, v132
	v_add_f32_e32 v132, v135, v133
	v_fmamk_f32 v133, v130, 0xbc800000, v29
	v_fmamk_f32 v135, v130, 0xbc800000, v27
	v_add_f32_e32 v131, v132, v131
	v_fmamk_f32 v132, v130, 0xbc800000, v28
	v_fmamk_f32 v134, v130, 0xbc800000, v26
	v_mul_f32_e32 v135, v135, v135
	v_mul_f32_e32 v133, v133, v133
	v_fmac_f32_e32 v135, v134, v134
	v_fmac_f32_e32 v133, v132, v132
	v_add_f32_e32 v132, v135, v133
	v_add_f32_e32 v131, v132, v131
	ds_bpermute_b32 v132, v169, v131
	s_waitcnt lgkmcnt(0)
	v_add_f32_e32 v131, v131, v132
	ds_bpermute_b32 v132, v171, v131
	s_and_saveexec_b64 s[0:1], vcc
	s_cbranch_execz .LBB0_3258
	s_lshl_b32 s9, s17, 11
	s_add_i32 s9, s8, s9
	v_mul_f32_e32 v130, 0x3c800000, v130
	v_lshl_add_u32 v133, v168, 5, s9
	s_waitcnt lgkmcnt(0)
	v_add_f32_e32 v131, v131, v132
	ds_write_b64 v133, v[130:131] offset:5120
.LBB0_3258:
	s_or_b64 exec, exec, s[0:1]
	s_waitcnt lgkmcnt(0)
	v_add_f32_e32 v130, v99, v98
	v_add_f32_e32 v131, v100, v101
	v_add_f32_e32 v132, v95, v94
	v_add_f32_e32 v133, v96, v97
	v_add_f32_e32 v130, v130, v131
	v_pk_add_f32 v[132:133], v[132:133], v[132:133] op_sel_hi:[0,1]
	v_add_f32_e32 v131, 0, v130
	v_add_f32_e32 v135, v62, v63
	v_add_f32_e32 v137, v64, v65
	v_mov_b32_e32 v134, v30
	v_mov_b32_e32 v136, v31
	v_mov_b32_e32 v132, v32
	v_mov_b32_e32 v130, v33
	v_pk_add_f32 v[134:135], v[134:135], v[136:137]
	v_pk_add_f32 v[130:131], v[132:133], v[130:131]
	s_nop 0
	v_pk_add_f32 v[130:131], v[134:135], v[130:131]
	s_nop 0
	v_add_f32_e32 v130, v130, v131
	ds_bpermute_b32 v131, v169, v130
	s_waitcnt lgkmcnt(0)
	v_add_f32_e32 v130, v130, v131
	ds_bpermute_b32 v131, v171, v130
	s_waitcnt lgkmcnt(0)
	v_add_f32_e32 v130, v130, v131
	v_fmamk_f32 v132, v130, 0xbc800000, v101
	v_fmamk_f32 v134, v130, 0xbc800000, v99
	v_fmamk_f32 v131, v130, 0xbc800000, v100
	v_fmamk_f32 v133, v130, 0xbc800000, v98
	v_mul_f32_e32 v134, v134, v134
	v_mul_f32_e32 v132, v132, v132
	v_fmac_f32_e32 v134, v133, v133
	v_fmac_f32_e32 v132, v131, v131
	v_fmamk_f32 v133, v130, 0xbc800000, v97
	v_fmamk_f32 v135, v130, 0xbc800000, v95
	v_add_f32_e32 v131, v134, v132
	v_fmamk_f32 v132, v130, 0xbc800000, v96
	v_fmamk_f32 v134, v130, 0xbc800000, v94
	v_mul_f32_e32 v135, v135, v135
	v_mul_f32_e32 v133, v133, v133
	v_fmac_f32_e32 v135, v134, v134
	v_fmac_f32_e32 v133, v132, v132
	v_add_f32_e32 v132, v135, v133
	v_fmamk_f32 v133, v130, 0xbc800000, v65
	v_fmamk_f32 v135, v130, 0xbc800000, v63
	v_add_f32_e32 v131, v131, v132
	v_fmamk_f32 v132, v130, 0xbc800000, v64
	v_fmamk_f32 v134, v130, 0xbc800000, v62
	v_mul_f32_e32 v135, v135, v135
	v_mul_f32_e32 v133, v133, v133
	v_fmac_f32_e32 v135, v134, v134
	v_fmac_f32_e32 v133, v132, v132
	v_add_f32_e32 v132, v135, v133
	v_fmamk_f32 v133, v130, 0xbc800000, v33
	v_fmamk_f32 v135, v130, 0xbc800000, v31
	v_add_f32_e32 v131, v132, v131
	v_fmamk_f32 v132, v130, 0xbc800000, v32
	v_fmamk_f32 v134, v130, 0xbc800000, v30
	v_mul_f32_e32 v135, v135, v135
	v_mul_f32_e32 v133, v133, v133
	v_fmac_f32_e32 v135, v134, v134
	v_fmac_f32_e32 v133, v132, v132
	v_add_f32_e32 v132, v135, v133
	v_add_f32_e32 v131, v132, v131
	ds_bpermute_b32 v132, v169, v131
	s_waitcnt lgkmcnt(0)
	v_add_f32_e32 v131, v131, v132
	ds_bpermute_b32 v132, v171, v131
	s_and_saveexec_b64 s[0:1], vcc
	s_cbranch_execz .LBB0_3260
	s_lshl_b32 s9, s17, 11
	s_add_i32 s8, s8, s9
	v_mul_f32_e32 v130, 0x3c800000, v130
	v_lshl_add_u32 v133, v168, 5, s8
	s_waitcnt lgkmcnt(0)
	v_add_f32_e32 v131, v131, v132
	ds_write_b64 v133, v[130:131] offset:5632
